# RWKV scans: rolling LDS prefetch + one address base per iteration + coalesced waits in both step loops; w0/a0 constant loads hoisted out of the chunk loop (chunk-top wait vmcnt(2)); secondary WG on a
# speedup vs baseline: 1.0242x; 1.0151x over previous
.LBB0_393:
	s_or_b64 exec, exec, s[10:11]
	s_waitcnt vmcnt(0)
	v_readfirstlane_b32 s2, v1
	v_mov_b32_e32 v1, 0x11ff4
	s_nop 0
	v_add_u32_e32 v0, s2, v0
	ds_write_b32 v1, v0
	v_cmp_ne_u32_e32 vcc, 0, v0
	s_cbranch_vccz .Lmix_sec_done
	s_mov_b32 s2, 0
.Lmix_sec_wait:
	global_load_dword v3, v2, s[12:13] sc1
	s_waitcnt vmcnt(0)
	v_readfirstlane_b32 s8, v3
	s_lshr_b32 s8, s8, 24
	s_cmp_lg_u32 s8, 0
	s_cbranch_scc1 .Lmix_sec_done
	s_sleep 16
	s_add_i32 s2, s2, 1
	s_cmp_lt_u32 s2, 0x4000
	s_cbranch_scc1 .Lmix_sec_wait
.Lmix_sec_done:
.LBB0_394:
	s_or_b64 exec, exec, s[6:7]
	s_lshl_b32 s88, s82, 1
	s_mov_b32 s89, s27
	s_lshl_b64 s[6:7], s[88:89], 2
	s_add_u32 s2, s86, s6
	s_addc_u32 s6, s87, s7
	s_add_u32 s90, s2, 0x7e000
	s_addc_u32 s91, s6, 0
	s_add_u32 s25, s86, 0x24c1000
	s_addc_u32 s46, s87, 0
	s_add_u32 s2, s86, 0x2bc1000
	v_writelane_b32 v255, s2, 35
	s_addc_u32 s2, s87, 0
	s_add_u32 s8, s86, 0x62c1000
	v_writelane_b32 v255, s2, 36
	s_addc_u32 s9, s87, 0
	v_writelane_b32 v255, s8, 31
	s_add_u32 s2, s86, 0x32c1000
	v_mov_b32_e32 v0, 0x11ff4
	v_writelane_b32 v255, s9, 32
	v_writelane_b32 v255, s2, 37
	s_addc_u32 s2, s87, 0
	s_add_u32 s8, s86, 0x4ac1000
	v_writelane_b32 v255, s2, 38
	s_addc_u32 s9, s87, 0
	v_writelane_b32 v255, s8, 39
	s_waitcnt lgkmcnt(0)
	s_barrier
	v_writelane_b32 v255, s9, 40
	s_add_u32 s8, s86, 0x2441000
	s_addc_u32 s9, s87, 0
	v_writelane_b32 v255, s8, 41
	ds_read_b32 v0, v0
	s_nop 0
	v_writelane_b32 v255, s9, 42
	s_lshl_b32 s8, s82, 9
	s_add_u32 s89, s86, 0xe0c1000
	s_addc_u32 s99, s87, 0
	s_add_u32 s96, s86, 0x80000
	s_addc_u32 s97, s87, 0
	s_add_u32 s92, s86, 0x2461000
	s_addc_u32 s93, s87, 0
	s_add_u32 s83, s86, 0x2481000
	s_addc_u32 s94, s87, 0
	s_add_u32 s44, s86, 0x86c1000
	s_addc_u32 s45, s87, 0
	s_mov_b32 s9, s27
	s_add_u32 s40, s86, 0xcec1000
	v_writelane_b32 v255, s8, 33
	s_addc_u32 s41, s87, 0
	s_add_u32 s2, s86, 0x26c1000
	v_writelane_b32 v255, s9, 34
	v_writelane_b32 v255, s2, 29
	s_addc_u32 s2, s87, 0
	v_writelane_b32 v255, s2, 30
	s_add_u32 s2, s86, 0x2dc1000
	v_writelane_b32 v255, s2, 43
	s_addc_u32 s2, s87, 0
	v_writelane_b32 v255, s2, 44
	s_add_u32 s2, s86, 0x24c3000
	v_writelane_b32 v255, s2, 45
	s_addc_u32 s2, s87, 0
	v_writelane_b32 v255, s2, 46
	s_add_u32 s2, s86, 0x2bc1080
	v_writelane_b32 v255, s2, 47
	s_addc_u32 s2, s87, 0
	v_writelane_b32 v255, s2, 48
	s_add_u32 s2, s86, 0x26c3000
	v_writelane_b32 v255, s2, 49
	s_addc_u32 s2, s87, 0
	v_writelane_b32 v255, s2, 50
	s_add_u32 s2, s86, 0x2dc1080
	v_writelane_b32 v255, s2, 51
	s_addc_u32 s2, s87, 0
	s_waitcnt lgkmcnt(0)
	v_cmp_ne_u32_e64 s[6:7], 0, v0
	v_writelane_b32 v255, s2, 52
	s_mov_b64 s[30:31], -1
	s_mov_b64 s[28:29], -1
	s_branch .LBB0_396

.LBB0_411:
	s_or_b64 exec, exec, s[10:11]
	s_waitcnt vmcnt(0)
	v_readfirstlane_b32 s2, v1
	s_nop 1
	v_add_u32_e32 v0, s2, v0
	s_movk_i32 s2, 0x80
	v_cmp_gt_i32_e32 vcc, s2, v0
	s_and_b64 s[10:11], vcc, exec
	s_nop 0
	v_cndmask_b32_e32 v0, -1, v0, vcc
	s_cmp_lg_u64 s[10:11], 0
	s_cbranch_scc1 .Lmix_nopub
	s_getreg_b32 s14, hwreg(HW_REG_HW_ID)
	s_getreg_b32 s15, hwreg(HW_REG_XCC_ID, 0, 4)
	s_bfe_u32 s14, s14, 0x80008
	s_lshl_b32 s15, s15, 8
	s_and_b32 s15, s15, 0xf00
	s_or_b32 s14, s14, s15
	s_lshl_b32 s14, s14, 2
	s_lshl_b32 s15, s82, 14
	s_add_i32 s14, s14, s15
	s_lshl_b32 s15, s82, 3
	s_sub_i32 s14, s14, s15
	s_sub_i32 s14, s14, 0xe000
	s_ashr_i32 s15, s14, 31
	s_add_u32 s14, s90, s14
	s_addc_u32 s15, s91, s15
	v_mov_b32_e32 v1, 0x1000000
	global_atomic_add v149, v1, s[14:15]
.Lmix_nopub:
.LBB0_412:
	s_or_b64 exec, exec, s[12:13]
	v_cmp_gt_i32_e32 vcc, 0, v0
	s_and_b64 s[14:15], vcc, s[30:31]
	s_mov_b64 s[12:13], s[30:31]
	s_and_saveexec_b64 s[16:17], s[14:15]
	s_cbranch_execz .LBB0_416
	s_mov_b64 s[14:15], exec
	v_mbcnt_lo_u32_b32 v0, s14, 0
	v_mbcnt_hi_u32_b32 v0, s15, v0
	v_cmp_eq_u32_e32 vcc, 0, v0
	s_and_saveexec_b64 s[12:13], vcc
	s_cbranch_execz .LBB0_415
	s_bcnt1_i32_b64 s2, s[14:15]
	v_mov_b32_e32 v1, s2
	global_atomic_add v1, v149, v1, s[90:91] offset:4 sc0

.LBB0_446:
	s_or_b64 exec, exec, s[16:17]
	s_lshl_b32 s2, s33, 16
	s_add_u32 s14, s92, s2
	s_addc_u32 s15, s93, 0
	v_lshlrev_b64 v[4:5], 7, v[148:149]
	v_lshl_add_u64 v[6:7], s[14:15], 0, v[4:5]
	s_add_u32 s14, s83, s2
	s_addc_u32 s15, s94, 0
	v_lshl_add_u64 v[4:5], s[14:15], 0, v[4:5]
	s_lshl_b64 s[14:15], s[26:27], 11
	s_waitcnt lgkmcnt(0)
	s_add_u32 s12, s12, s14
	v_mov_b64_e32 v[8:9], s[44:45]
	s_addc_u32 s13, s13, s15
	v_mad_u64_u32 v[10:11], s[16:17], v2, s43, v[8:9]
	s_add_u32 s14, s22, s14
	v_and_b32_e32 v68, 7, v52
	v_mad_i32_i24 v11, v3, s43, v11
	v_lshlrev_b64 v[56:57], 1, v[148:149]
	v_lshlrev_b64 v[2:3], 9, v[2:3]
	v_lshlrev_b64 v[54:55], 2, v[148:149]
	s_addc_u32 s15, s23, s15
	v_lshl_add_u64 v[10:11], v[10:11], 0, v[56:57]
	v_lshlrev_b32_e32 v148, 4, v68
	v_lshl_add_u64 v[2:3], s[40:41], 0, v[2:3]
	s_lshl_b32 s26, s33, 8
	v_lshl_add_u64 v[10:11], v[10:11], 0, v[148:149]
	v_lshl_add_u64 v[2:3], v[2:3], 0, s[26:27]
	v_mad_u64_u32 v[8:9], s[16:17], v0, s43, v[8:9]
	global_load_dwordx4 v[104:107], v[10:11], off
	global_load_dwordx4 v[88:91], v[10:11], off offset:1024
	v_lshl_add_u64 v[2:3], v[2:3], 0, v[148:149]
	global_load_dwordx4 v[92:95], v[10:11], off offset:2048
	global_load_dwordx4 v[108:111], v[2:3], off
	v_mov_b32_e32 v10, v9
	v_mad_u64_u32 v[10:11], s[16:17], v1, s43, v[10:11]
	v_bfe_u32 v67, v52, 4, 2
	v_mov_b32_e32 v9, v10
	v_lshl_add_u64 v[8:9], v[8:9], 0, v[56:57]
	v_lshlrev_b64 v[0:1], 9, v[0:1]
	v_lshlrev_b32_e32 v58, 4, v67
	v_mov_b32_e32 v59, v149
	v_and_b32_e32 v66, 15, v52
	v_lshl_add_u64 v[8:9], v[8:9], 0, v[148:149]
	global_load_dwordx4 v[112:115], v[2:3], off offset:128
	global_load_dwordx4 v[32:35], v[8:9], off
	global_load_dwordx4 v[36:39], v[8:9], off offset:1024
	global_load_dwordx4 v[40:43], v[8:9], off offset:2048
	v_lshl_add_u64 v[0:1], s[40:41], 0, v[0:1]
	v_lshl_add_u64 v[2:3], v[4:5], 0, v[58:59]
	v_ashrrev_i32_e32 v4, 2, v52
	s_movk_i32 s2, 0xffe0
	v_lshl_add_u64 v[0:1], v[0:1], 0, s[26:27]
	v_and_or_b32 v60, v4, s2, v66
	v_lshl_add_u64 v[0:1], v[0:1], 0, v[148:149]
	v_ashrrev_i32_e32 v61, 31, v60
	v_or_b32_e32 v62, 16, v60
	global_load_dwordx4 v[44:47], v[0:1], off
	global_load_dwordx4 v[48:51], v[0:1], off offset:128
	v_lshl_add_u64 v[0:1], v[6:7], 0, v[58:59]
	v_lshlrev_b64 v[4:5], 7, v[60:61]
	v_ashrrev_i32_e32 v63, 31, v62
	v_lshl_add_u64 v[6:7], v[0:1], 0, v[4:5]
	v_lshl_add_u64 v[12:13], v[2:3], 0, v[4:5]
	v_lshlrev_b64 v[4:5], 7, v[62:63]
	v_lshl_add_u64 v[20:21], v[0:1], 0, v[4:5]
	v_lshl_add_u64 v[28:29], v[2:3], 0, v[4:5]
	global_load_dwordx4 v[0:3], v[6:7], off
	s_nop 0
	global_load_dwordx4 v[4:7], v[6:7], off offset:64
	s_nop 0
	global_load_dwordx4 v[8:11], v[12:13], off
	s_nop 0
	global_load_dwordx4 v[12:15], v[12:13], off offset:64
	s_nop 0
	global_load_dwordx4 v[16:19], v[20:21], off
	s_nop 0
	global_load_dwordx4 v[20:23], v[20:21], off offset:64
	s_nop 0
	global_load_dwordx4 v[24:27], v[28:29], off
	s_nop 0
	global_load_dwordx4 v[28:31], v[28:29], off offset:64
	s_movk_i32 s2, 0x70
	v_lshlrev_b32_e32 v59, 5, v68
	v_mul_lo_u32 v63, v196, s98
	v_mul_lo_u32 v69, v196, s2
	v_lshrrev_b32_e32 v53, 29, v53
	v_or_b32_e32 v197, 0x10400, v59
	s_add_u32 s16, s40, s26
	v_add3_u32 v199, v63, v69, v59
	v_lshrrev_b32_e32 v59, 2, v52
	v_add_u32_e32 v53, v52, v53
	s_addc_u32 s17, s41, 0
	v_add_u32_e32 v198, v63, v148
	v_and_b32_e32 v63, 16, v59
	s_mul_i32 s2, s33, 0x1800000
	v_ashrrev_i32_e32 v150, 3, v53
	v_and_b32_e32 v53, -8, v53
	v_or_b32_e32 v59, v63, v66
	s_add_u32 s22, s89, s2
	v_sub_u32_e32 v53, v52, v53
	v_mul_u32_u24_e32 v59, 0x48, v59
	s_addc_u32 s23, s99, 0
	v_lshlrev_b32_e32 v152, 3, v53
	v_lshl_add_u32 v200, v59, 1, v58
	v_lshlrev_b32_e32 v201, 5, v53
	v_lshl_add_u64 v[58:59], s[22:23], 0, v[56:57]
	s_lshl_b32 s2, s36, 3
	v_lshlrev_b32_e32 v53, 6, v63
	v_lshl_add_u64 v[64:65], s[12:13], 0, v[54:55]
	v_lshl_add_u64 v[54:55], s[14:15], 0, v[54:55]
	v_lshl_add_u64 v[154:155], v[58:59], 0, v[148:149]
	s_add_u32 s2, s96, s2
	v_lshlrev_b64 v[58:59], 2, v[60:61]
	v_lshl_or_b32 v53, v67, 8, v53
	s_addc_u32 s15, s97, 0
	s_lshl_b32 s22, s33, 2
	v_lshl_add_u64 v[158:159], v[54:55], 0, v[58:59]
	v_add_lshl_u32 v203, v53, v60, 2
	v_add_lshl_u32 v204, v53, v62, 2
	v_lshl_add_u64 v[54:55], s[44:45], 0, v[56:57]
	v_lshlrev_b32_e32 v52, 5, v52
	v_lshlrev_b32_e32 v53, 8, v150
	v_lshlrev_b32_e32 v202, 2, v150
	s_add_u32 s22, s2, s22
	v_lshl_add_u64 v[160:161], v[54:55], 0, v[148:149]
	v_lshl_add_u64 v[162:163], s[16:17], 0, v[148:149]
	v_sub_u32_e32 v52, v52, v53
	v_mov_b32_e32 v148, v149
	v_ashrrev_i32_e32 v151, 31, v150
	v_ashrrev_i32_e32 v153, 31, v152
	s_mov_b32 s14, 0
	v_cmp_eq_u32_e64 s[12:13], 0, v68
	s_addc_u32 s23, s15, 0
	v_lshl_add_u64 v[156:157], v[64:65], 0, v[58:59]
	v_add_u32_e32 v205, 0x4100, v202
	v_add_u32_e32 v206, 0x100, v52
	v_mov_b64_e32 v[84:85], v[148:149]
	v_mov_b64_e32 v[86:87], v[148:149]
	v_mov_b64_e32 v[80:81], v[148:149]
	v_mov_b64_e32 v[82:83], v[148:149]
	v_mov_b64_e32 v[76:77], v[148:149]
	v_mov_b64_e32 v[78:79], v[148:149]
	v_mov_b64_e32 v[72:73], v[148:149]
	v_mov_b64_e32 v[74:75], v[148:149]
	global_load_dword v240, v[156:157], off
	global_load_dword v241, v[158:159], off
	global_load_dword v242, v[156:157], off offset:64
	global_load_dword v243, v[158:159], off offset:64
	s_waitcnt vmcnt(0)
.LBB0_447:
	v_lshl_add_u32 v148, s14, 5, v196
	v_cmp_gt_i32_e32 vcc, 1, v148
	s_waitcnt vmcnt(2)
	v_and_b32_e32 v185, 0xffff0000, v32
	v_lshlrev_b32_e32 v184, 16, v32
	v_and_b32_e32 v181, 0xffff0000, v33
	v_lshlrev_b32_e32 v180, 16, v33
	v_and_b32_e32 v177, 0xffff0000, v34
	v_lshlrev_b32_e32 v176, 16, v34
	v_and_b32_e32 v173, 0xffff0000, v35
	v_lshlrev_b32_e32 v172, 16, v35
	s_waitcnt vmcnt(11)
	v_and_b32_e32 v165, 0xffff0000, v36
	v_lshlrev_b32_e32 v164, 16, v36
	v_and_b32_e32 v167, 0xffff0000, v37
	v_lshlrev_b32_e32 v166, 16, v37
	v_and_b32_e32 v169, 0xffff0000, v38
	v_lshlrev_b32_e32 v168, 16, v38
	v_and_b32_e32 v171, 0xffff0000, v39
	v_lshlrev_b32_e32 v170, 16, v39
	s_waitcnt vmcnt(10)
	v_and_b32_e32 v191, 0xffff0000, v40
	v_lshlrev_b32_e32 v190, 16, v40
	v_and_b32_e32 v187, 0xffff0000, v41
	v_lshlrev_b32_e32 v186, 16, v41
	v_and_b32_e32 v179, 0xffff0000, v42
	v_lshlrev_b32_e32 v178, 16, v42
	v_and_b32_e32 v175, 0xffff0000, v43
	v_lshlrev_b32_e32 v174, 16, v43
	s_waitcnt vmcnt(9)
	v_and_b32_e32 v213, 0xffff0000, v44
	v_lshlrev_b32_e32 v224, 16, v44
	v_and_b32_e32 v211, 0xffff0000, v45
	v_lshlrev_b32_e32 v212, 16, v45
	v_and_b32_e32 v209, 0xffff0000, v46
	v_lshlrev_b32_e32 v210, 16, v46
	v_and_b32_e32 v207, 0xffff0000, v47
	v_lshlrev_b32_e32 v208, 16, v47
	s_waitcnt vmcnt(8)
	v_and_b32_e32 v195, 0xffff0000, v48
	v_lshlrev_b32_e32 v194, 16, v48
	v_and_b32_e32 v193, 0xffff0000, v49
	v_lshlrev_b32_e32 v192, 16, v49
	v_and_b32_e32 v189, 0xffff0000, v50
	v_lshlrev_b32_e32 v188, 16, v50
	v_and_b32_e32 v183, 0xffff0000, v51
	v_lshlrev_b32_e32 v182, 16, v51
	s_and_saveexec_b64 s[16:17], vcc
	s_cbranch_execz .LBB0_449
	v_mov_b32_e32 v184, 0
	v_mov_b32_e32 v185, v184
	v_mov_b32_e32 v180, v184
	v_mov_b32_e32 v181, v184
	v_mov_b32_e32 v176, v184
	v_mov_b32_e32 v177, v184
	v_mov_b32_e32 v172, v184
	v_mov_b32_e32 v173, v184
	v_mov_b32_e32 v190, v184
	v_mov_b32_e32 v191, v184
	v_mov_b32_e32 v186, v184
	v_mov_b32_e32 v187, v184
	v_mov_b32_e32 v178, v184
	v_mov_b32_e32 v179, v184
	v_mov_b32_e32 v174, v184
	v_mov_b32_e32 v175, v184
	v_mov_b32_e32 v164, v184
	v_mov_b32_e32 v165, v184
	v_mov_b32_e32 v166, v184
	v_mov_b32_e32 v167, v184
	v_mov_b32_e32 v168, v184
	v_mov_b32_e32 v169, v184
	v_mov_b32_e32 v170, v184
	v_mov_b32_e32 v171, v184
	v_mov_b32_e32 v182, v184
	v_mov_b32_e32 v183, v184
	v_mov_b32_e32 v188, v184
	v_mov_b32_e32 v189, v184
	v_mov_b32_e32 v192, v184
	v_mov_b32_e32 v193, v184
	v_mov_b32_e32 v194, v184
	v_mov_b32_e32 v195, v184
	v_mov_b32_e32 v224, v184
	v_mov_b32_e32 v213, v184
	v_mov_b32_e32 v212, v184
	v_mov_b32_e32 v211, v184
	v_mov_b32_e32 v210, v184
	v_mov_b32_e32 v209, v184
	v_mov_b32_e32 v208, v184
	v_mov_b32_e32 v207, v184

.LBB0_456:
	v_lshlrev_b32_e32 v225, 16, v108
	v_and_b32_e32 v230, 0xffff0000, v108
	v_lshlrev_b32_e32 v231, 16, v109
	v_and_b32_e32 v232, 0xffff0000, v109
	v_lshlrev_b32_e32 v233, 16, v110
	v_and_b32_e32 v234, 0xffff0000, v110
	v_lshlrev_b32_e32 v235, 16, v111
	v_and_b32_e32 v236, 0xffff0000, v111
	v_and_b32_e32 v111, 0xffff0000, v112
	v_lshlrev_b32_e32 v110, 16, v112
	v_and_b32_e32 v215, 0xffff0000, v113
	v_lshlrev_b32_e32 v214, 16, v113
	v_and_b32_e32 v217, 0xffff0000, v114
	v_lshlrev_b32_e32 v216, 16, v114
	v_and_b32_e32 v219, 0xffff0000, v115
	v_lshlrev_b32_e32 v218, 16, v115
	v_and_b32_e32 v109, 0xffff0000, v104
	v_lshlrev_b32_e32 v108, 16, v104
	v_and_b32_e32 v113, 0xffff0000, v105
	v_lshlrev_b32_e32 v112, 16, v105
	v_and_b32_e32 v105, 0xffff0000, v106
	v_lshlrev_b32_e32 v104, 16, v106
	v_and_b32_e32 v115, 0xffff0000, v107
	v_lshlrev_b32_e32 v114, 16, v107
	v_and_b32_e32 v107, 0xffff0000, v92
	v_lshlrev_b32_e32 v106, 16, v92
	v_sub_f32_e32 v92, v224, v225
	v_and_b32_e32 v221, 0xffff0000, v93
	v_lshlrev_b32_e32 v220, 16, v93
	v_and_b32_e32 v227, 0xffff0000, v94
	v_lshlrev_b32_e32 v226, 16, v94
	v_and_b32_e32 v229, 0xffff0000, v95
	v_lshlrev_b32_e32 v228, 16, v95
	s_waitcnt lgkmcnt(7)
	v_fmac_f32_e32 v225, v92, v132
	v_pk_add_f32 v[92:93], v[184:185], v[108:109] neg_lo:[0,1] neg_hi:[0,1]
	v_pk_add_f32 v[94:95], v[190:191], v[106:107] neg_lo:[0,1] neg_hi:[0,1]
	v_pk_fma_f32 v[92:93], v[92:93], v[136:137], v[108:109]
	s_waitcnt lgkmcnt(3)
	v_pk_fma_f32 v[108:109], v[94:95], v[144:145], v[106:107]
	v_sub_f32_e32 v94, v213, v230
	v_fmac_f32_e32 v230, v94, v133
	v_pk_add_f32 v[94:95], v[194:195], v[110:111] neg_lo:[0,1] neg_hi:[0,1]
	v_pk_add_f32 v[106:107], v[186:187], v[220:221] neg_lo:[0,1] neg_hi:[0,1]
	s_waitcnt lgkmcnt(1)
	v_pk_fma_f32 v[132:133], v[94:95], v[140:141], v[110:111]
	v_pk_fma_f32 v[110:111], v[106:107], v[146:147], v[220:221]
	v_sub_f32_e32 v106, v211, v232
	v_sub_f32_e32 v94, v212, v231
	v_fmac_f32_e32 v232, v106, v135
	v_pk_add_f32 v[106:107], v[192:193], v[214:215] neg_lo:[0,1] neg_hi:[0,1]
	v_fmac_f32_e32 v231, v94, v134
	v_pk_fma_f32 v[134:135], v[106:107], v[142:143], v[214:215]
	v_sub_f32_e32 v106, v210, v233
	v_fmac_f32_e32 v233, v106, v120
	v_pk_add_f32 v[106:107], v[176:177], v[104:105] neg_lo:[0,1] neg_hi:[0,1]
	v_pk_add_f32 v[94:95], v[180:181], v[112:113] neg_lo:[0,1] neg_hi:[0,1]
	v_pk_fma_f32 v[104:105], v[106:107], v[124:125], v[104:105]
	v_pk_add_f32 v[106:107], v[178:179], v[226:227] neg_lo:[0,1] neg_hi:[0,1]
	v_pk_fma_f32 v[94:95], v[94:95], v[138:139], v[112:113]
	v_pk_fma_f32 v[112:113], v[106:107], v[128:129], v[226:227]
	v_sub_f32_e32 v106, v209, v234
	v_fmac_f32_e32 v234, v106, v121
	v_pk_add_f32 v[106:107], v[188:189], v[216:217] neg_lo:[0,1] neg_hi:[0,1]
	v_and_b32_e32 v137, 0xffff0000, v90
	s_waitcnt lgkmcnt(0)
	v_pk_fma_f32 v[120:121], v[106:107], v[116:117], v[216:217]
	v_sub_f32_e32 v106, v208, v235
	v_fmac_f32_e32 v235, v106, v122
	v_add_f32_e32 v122, v225, v225
	v_mul_f32_e32 v122, 0x3fb8aa3b, v122
	v_exp_f32_e32 v124, v122
	v_add_f32_e32 v122, v230, v230
	v_mul_f32_e32 v122, 0x3fb8aa3b, v122
	v_exp_f32_e32 v125, v122
	v_sub_f32_e32 v116, v207, v236
	v_pk_add_f32 v[106:107], v[172:173], v[114:115] neg_lo:[0,1] neg_hi:[0,1]
	v_fmac_f32_e32 v236, v116, v123
	v_pk_add_f32 v[116:117], v[182:183], v[218:219] neg_lo:[0,1] neg_hi:[0,1]
	v_pk_fma_f32 v[106:107], v[106:107], v[126:127], v[114:115]
	v_pk_fma_f32 v[122:123], v[116:117], v[118:119], v[218:219]
	v_add_f32_e32 v116, 1.0, v124
	v_add_f32_e32 v117, 1.0, v125
	v_add_f32_e32 v118, v231, v231
	v_add_f32_e32 v119, v232, v232
	v_add_f32_e32 v124, v233, v233
	v_add_f32_e32 v125, v234, v234
	v_add_f32_e32 v126, v235, v235
	v_add_f32_e32 v127, v236, v236
	v_mul_f32_e32 v118, 0x3fb8aa3b, v118
	v_mul_f32_e32 v119, 0x3fb8aa3b, v119
	v_mul_f32_e32 v124, 0x3fb8aa3b, v124
	v_mul_f32_e32 v125, 0x3fb8aa3b, v125
	v_mul_f32_e32 v126, 0x3fb8aa3b, v126
	v_mul_f32_e32 v127, 0x3fb8aa3b, v127
	v_exp_f32_e32 v118, v118
	v_exp_f32_e32 v119, v119
	v_exp_f32_e32 v124, v124
	v_exp_f32_e32 v125, v125
	v_exp_f32_e32 v126, v126
	v_exp_f32_e32 v127, v127
	v_add_f32_e32 v118, 1.0, v118
	v_add_f32_e32 v119, 1.0, v119
	v_add_f32_e32 v124, 1.0, v124
	v_add_f32_e32 v125, 1.0, v125
	v_add_f32_e32 v126, 1.0, v126
	v_add_f32_e32 v127, 1.0, v127
	v_rcp_f32_e32 v116, v116
	v_rcp_f32_e32 v117, v117
	v_rcp_f32_e32 v118, v118
	v_rcp_f32_e32 v119, v119
	v_rcp_f32_e32 v124, v124
	v_rcp_f32_e32 v125, v125
	v_rcp_f32_e32 v126, v126
	v_rcp_f32_e32 v127, v127
	v_pk_fma_f32 v[116:117], v[116:117], 2.0, 1.0 op_sel_hi:[1,0,0] neg_lo:[1,0,0] neg_hi:[1,0,0]
	v_pk_fma_f32 v[118:119], v[118:119], 2.0, 1.0 op_sel_hi:[1,0,0] neg_lo:[1,0,0] neg_hi:[1,0,0]
	v_pk_fma_f32 v[124:125], v[124:125], 2.0, 1.0 op_sel_hi:[1,0,0] neg_lo:[1,0,0] neg_hi:[1,0,0]
	v_pk_fma_f32 v[126:127], v[126:127], 2.0, 1.0 op_sel_hi:[1,0,0] neg_lo:[1,0,0] neg_hi:[1,0,0]
	v_cvt_pk_bf16_f32 v116, v116, v117
	v_cvt_pk_bf16_f32 v117, v118, v119
	v_cvt_pk_bf16_f32 v118, v124, v125
	v_cvt_pk_bf16_f32 v119, v126, v127
	v_pk_add_f32 v[114:115], v[174:175], v[228:229] neg_lo:[0,1] neg_hi:[0,1]
	ds_write_b128 v198, v[116:119] offset:57344
	v_cvt_pk_bf16_f32 v116, v132, v133
	v_cvt_pk_bf16_f32 v117, v134, v135
	v_cvt_pk_bf16_f32 v118, v120, v121
	v_cvt_pk_bf16_f32 v119, v122, v123
	v_pk_fma_f32 v[114:115], v[114:115], v[130:131], v[228:229]
	ds_write_b128 v198, v[116:119] offset:61952
	ds_write_b128 v199, v[92:95]
	ds_write_b128 v199, v[108:111] offset:16384
	ds_write_b128 v199, v[104:107] offset:16
	ds_write_b128 v199, v[112:115] offset:16400
	s_waitcnt lgkmcnt(0)
	s_barrier
	ds_read_b128 v[108:111], v200 offset:57344
	ds_read_b128 v[116:119], v200 offset:57408
	ds_read_b128 v[112:115], v200 offset:61952
	ds_read_b128 v[124:127], v200 offset:62016
	s_waitcnt lgkmcnt(3)
	v_mfma_f32_16x16x32_bf16 v[120:123], v[108:111], v[0:3], 0
	v_and_b32_e32 v133, 0xffff0000, v88
	v_lshlrev_b32_e32 v132, 16, v88
	v_and_b32_e32 v135, 0xffff0000, v89
	v_lshlrev_b32_e32 v134, 16, v89
	v_lshlrev_b32_e32 v136, 16, v90
	v_and_b32_e32 v139, 0xffff0000, v91
	v_lshlrev_b32_e32 v138, 16, v91
	s_nop 0
	v_mfma_f32_16x16x32_bf16 v[88:91], v[108:111], v[16:19], 0
	v_add_f32_e64 v108, v164, -v132
	v_add_f32_e64 v109, v165, -v133
	v_pk_fma_f32 v[132:133], v[108:109], v[100:101], v[132:133]
	v_pk_add_f32 v[100:101], v[166:167], v[134:135] neg_lo:[0,1] neg_hi:[0,1]
	s_waitcnt lgkmcnt(1)
	v_mfma_f32_16x16x32_bf16 v[128:131], v[112:115], v[8:11], 0
	v_fma_f32 v134, v100, v102, v134
	v_fma_f32 v135, v101, v103, v135
	v_mfma_f32_16x16x32_bf16 v[100:103], v[116:119], v[4:7], v[120:123]
	s_nop 0
	v_mfma_f32_16x16x32_bf16 v[108:111], v[112:115], v[24:27], 0
	v_add_f32_e64 v112, v168, -v136
	v_add_f32_e64 v113, v169, -v137
	s_nop 0
	s_nop 2
	v_add_f32_e32 v101, v101, v240
	v_add_f32_e32 v102, v102, v240
	v_mfma_f32_16x16x32_bf16 v[88:91], v[116:119], v[20:23], v[88:91]
	v_mul_f32_e32 v101, 0xbfb8aa3b, v101
	v_mul_f32_e32 v102, 0xbfb8aa3b, v102
	v_add_f32_e32 v103, v103, v240
	v_pk_fma_f32 v[136:137], v[112:113], v[96:97], v[136:137]
	v_pk_add_f32 v[96:97], v[170:171], v[138:139] neg_lo:[0,1] neg_hi:[0,1]
	v_exp_f32_e32 v101, v101
	v_exp_f32_e32 v102, v102
	v_mul_f32_e32 v103, 0xbfb8aa3b, v103
	v_pk_fma_f32 v[138:139], v[96:97], v[98:99], v[138:139]
	s_waitcnt lgkmcnt(0)
	v_mfma_f32_16x16x32_bf16 v[96:99], v[124:127], v[12:15], v[128:131]
	v_exp_f32_e32 v103, v103
	v_add_f32_e32 v100, v100, v240
	s_nop 0
	v_add_f32_e32 v88, v88, v242
	v_mul_f32_e32 v100, 0xbfb8aa3b, v100
	v_add_f32_e32 v101, 1.0, v101
	v_add_f32_e32 v102, 1.0, v102
	v_mul_f32_e32 v88, 0xbfb8aa3b, v88
	v_exp_f32_e32 v100, v100
	v_add_f32_e32 v96, v96, v241
	v_rcp_f32_e32 v101, v101
	v_rcp_f32_e32 v102, v102
	v_add_f32_e32 v103, 1.0, v103
	v_exp_f32_e32 v88, v88
	v_mul_f32_e32 v96, 0xbfb8aa3b, v96
	v_add_f32_e32 v98, v98, v241
	v_rcp_f32_e32 v103, v103
	v_add_f32_e32 v99, v99, v241
	v_exp_f32_e32 v96, v96
	v_mul_f32_e32 v98, 0xbfb8aa3b, v98
	v_mul_f32_e32 v99, 0xbfb8aa3b, v99
	v_exp_f32_e32 v98, v98
	v_exp_f32_e32 v99, v99
	v_add_f32_e32 v100, 1.0, v100
	v_mul_f32_e32 v101, 0xbf1b4598, v101
	v_mul_f32_e32 v102, 0xbf1b4598, v102
	v_add_f32_e32 v88, 1.0, v88
	v_rcp_f32_e32 v100, v100
	v_mul_f32_e32 v101, 0x3fb8aa3b, v101
	v_mul_f32_e32 v102, 0x3fb8aa3b, v102
	v_mul_f32_e32 v103, 0xbf1b4598, v103
	v_rcp_f32_e32 v88, v88
	v_mfma_f32_16x16x32_bf16 v[108:111], v[124:127], v[28:31], v[108:111]
	v_add_f32_e32 v96, 1.0, v96
	v_exp_f32_e32 v101, v101
	v_exp_f32_e32 v102, v102
	v_mul_f32_e32 v103, 0x3fb8aa3b, v103
	v_rcp_f32_e32 v96, v96
	v_add_f32_e32 v98, 1.0, v98
	v_exp_f32_e32 v103, v103
	v_add_f32_e32 v99, 1.0, v99
	v_rcp_f32_e32 v98, v98
	v_rcp_f32_e32 v99, v99
	v_mul_f32_e32 v100, 0xbf1b4598, v100
	v_mul_f32_e32 v88, 0xbf1b4598, v88
	v_add_f32_e32 v89, v89, v242
	v_add_f32_e32 v90, v90, v242
	v_mul_f32_e32 v100, 0x3fb8aa3b, v100
	ds_write2st64_b32 v203, v101, v102 offset0:97 offset1:98
	ds_write2st64_b32 v203, v103, v96 offset0:99 offset1:128
	ds_write2st64_b32 v203, v98, v99 offset0:130 offset1:131
	v_mul_f32_e32 v88, 0x3fb8aa3b, v88
	s_nop 0
	v_add_f32_e32 v98, v108, v243
	v_mul_f32_e32 v89, 0xbfb8aa3b, v89
	v_mul_f32_e32 v90, 0xbfb8aa3b, v90
	v_add_f32_e32 v91, v91, v242
	v_exp_f32_e32 v100, v100
	v_exp_f32_e32 v88, v88
	v_exp_f32_e32 v89, v89
	v_mul_f32_e32 v98, 0xbfb8aa3b, v98
	v_exp_f32_e32 v90, v90
	v_mul_f32_e32 v91, 0xbfb8aa3b, v91
	v_exp_f32_e32 v98, v98
	v_exp_f32_e32 v91, v91
	v_add_f32_e32 v97, v97, v241
	v_add_u32_e32 v96, 0x6000, v203
	v_mul_f32_e32 v97, 0xbfb8aa3b, v97
	ds_write2_b32 v96, v100, v88 offset1:16
	v_add_f32_e32 v88, 1.0, v89
	v_add_f32_e32 v90, 1.0, v90
	v_exp_f32_e32 v97, v97
	v_rcp_f32_e32 v88, v88
	v_add_f32_e32 v89, 1.0, v98
	v_add_f32_e32 v98, v109, v243
	v_rcp_f32_e32 v90, v90
	v_add_f32_e32 v91, 1.0, v91
	v_mul_f32_e32 v98, 0xbfb8aa3b, v98
	v_add_f32_e32 v99, v110, v243
	v_rcp_f32_e32 v91, v91
	v_add_f32_e32 v100, v111, v243
	v_exp_f32_e32 v98, v98
	v_mul_f32_e32 v99, 0xbfb8aa3b, v99
	v_mul_f32_e32 v100, 0xbfb8aa3b, v100
	v_exp_f32_e32 v99, v99
	v_exp_f32_e32 v100, v100
	v_add_f32_e32 v97, 1.0, v97
	v_mul_f32_e32 v88, 0xbf1b4598, v88
	v_mul_f32_e32 v90, 0xbf1b4598, v90
	v_rcp_f32_e32 v97, v97
	v_rcp_f32_e32 v89, v89
	v_mul_f32_e32 v88, 0x3fb8aa3b, v88
	v_mul_f32_e32 v90, 0x3fb8aa3b, v90
	v_mul_f32_e32 v91, 0xbf1b4598, v91
	v_sub_u32_e32 v112, 0xff, v148
	v_exp_f32_e32 v88, v88
	v_add_f32_e32 v98, 1.0, v98
	v_exp_f32_e32 v90, v90
	v_mul_f32_e32 v91, 0x3fb8aa3b, v91
	v_cndmask_b32_e64 v112, v112, v148, s[8:9]
	v_rcp_f32_e32 v98, v98
	v_add_f32_e32 v99, 1.0, v99
	v_exp_f32_e32 v91, v91
	v_add_f32_e32 v100, 1.0, v100
	v_ashrrev_i32_e32 v113, 31, v112
	v_add_u32_e32 v96, 0x8000, v203
	v_rcp_f32_e32 v99, v99
	v_rcp_f32_e32 v100, v100
	v_lshl_add_u64 v[128:129], v[112:113], 0, s[20:21]
	ds_write2_b32 v96, v89, v97 offset0:16 offset1:64
	ds_write2st64_b32 v204, v88, v90 offset0:97 offset1:98
	ds_write2st64_b32 v204, v91, v98 offset0:99 offset1:129
	ds_write2st64_b32 v204, v99, v100 offset0:130 offset1:131
	s_waitcnt lgkmcnt(0)
	s_barrier
	ds_read_b128 v[88:91], v197 offset:1280
	ds_read_b128 v[96:99], v197 offset:1792
	ds_read_b128 v[100:103], v197 offset:1808
	ds_read_b128 v[108:111], v197 offset:1296
	ds_read_b128 v[112:115], v199 offset:32768
	ds_read_b128 v[116:119], v197 offset:1536
	ds_read_b128 v[124:127], v197 offset:1552
	s_waitcnt lgkmcnt(6)
	v_pk_mul_f32 v[130:131], v[132:133], v[88:89]
	ds_read_b128 v[120:123], v199 offset:32784
	s_waitcnt lgkmcnt(3)
	v_pk_add_f32 v[88:89], v[112:113], -1.0 op_sel_hi:[1,0]
	v_pk_mul_f32 v[140:141], v[130:131], v[130:131]
	s_waitcnt lgkmcnt(2)
	v_pk_fma_f32 v[88:89], v[88:89], v[116:117], 1.0 op_sel_hi:[1,1,0]
	s_nop 0
	v_pk_mul_f32 v[88:89], v[132:133], v[88:89]
	s_nop 0
	v_pk_mul_f32 v[116:117], v[92:93], v[88:89]
	v_pk_mul_f32 v[92:93], v[134:135], v[90:91]
	v_pk_add_f32 v[90:91], v[114:115], -1.0 op_sel_hi:[1,0]
	v_pk_mul_f32 v[132:133], v[92:93], v[92:93]
	v_pk_fma_f32 v[90:91], v[90:91], v[118:119], 1.0 op_sel_hi:[1,1,0]
	s_nop 0
	v_pk_mul_f32 v[90:91], v[134:135], v[90:91]
	ds_write_b128 v199, v[88:91] offset:8192
	s_waitcnt lgkmcnt(1)
	v_pk_add_f32 v[88:89], v[120:121], -1.0 op_sel_hi:[1,0]
	v_pk_mul_f32 v[118:119], v[94:95], v[90:91]
	v_pk_fma_f32 v[88:89], v[88:89], v[124:125], 1.0 op_sel_hi:[1,1,0]
	v_pk_add_f32 v[124:125], v[122:123], -1.0 op_sel_hi:[1,0]
	v_pk_mul_f32 v[94:95], v[136:137], v[108:109]
	v_pk_fma_f32 v[124:125], v[124:125], v[126:127], 1.0 op_sel_hi:[1,1,0]
	v_add_f32_e32 v126, v140, v141
	v_add_f32_e32 v126, v126, v132
	v_pk_mul_f32 v[90:91], v[94:95], v[94:95]
	v_add_f32_e32 v126, v126, v133
	v_pk_mul_f32 v[108:109], v[138:139], v[110:111]
	v_add_f32_e32 v90, v126, v90
	v_pk_mul_f32 v[110:111], v[108:109], v[108:109]
	v_add_f32_e32 v90, v90, v91
	v_add_f32_e32 v90, v90, v110
	v_add_f32_e32 v90, v90, v111
	v_pk_mul_f32 v[88:89], v[136:137], v[88:89]
	s_nop 0
	v_add_f32_dpp v90, v90, v90 quad_perm:[1,0,3,2] row_mask:0xf bank_mask:0xf bound_ctrl:1
	v_pk_mul_f32 v[104:105], v[104:105], v[88:89]
	s_nop 0
	v_add_f32_dpp v90, v90, v90 quad_perm:[2,3,0,1] row_mask:0xf bank_mask:0xf bound_ctrl:1
	s_nop 1
	v_add_f32_dpp v90, v90, v90 row_half_mirror row_mask:0xf bank_mask:0xf bound_ctrl:1
	v_max_f32_e32 v90, 0x179abe15, v90
	v_rsq_f32_e32 v110, v90
	v_pk_mul_f32 v[90:91], v[138:139], v[124:125]
	ds_write_b128 v199, v[88:91] offset:8208
	v_pk_mul_f32 v[106:107], v[106:107], v[90:91]
	v_pk_mul_f32 v[124:125], v[130:131], v[110:111] op_sel_hi:[1,0]
	v_pk_mul_f32 v[126:127], v[92:93], v[110:111] op_sel_hi:[1,0]
	v_xor_b32_e32 v89, 0x80000000, v125
	v_xor_b32_e32 v88, 0x80000000, v124
	v_xor_b32_e32 v91, 0x80000000, v127
	v_xor_b32_e32 v90, 0x80000000, v126
	v_pk_mul_f32 v[130:131], v[94:95], v[110:111] op_sel_hi:[1,0]
	v_pk_mul_f32 v[108:109], v[108:109], v[110:111] op_sel_hi:[1,0]
	ds_write_b128 v199, v[88:91] offset:32768
	v_pk_mul_f32 v[88:89], v[112:113], v[124:125]
	v_pk_mul_f32 v[90:91], v[114:115], v[126:127]
	v_xor_b32_e32 v93, 0x80000000, v131
	v_xor_b32_e32 v92, 0x80000000, v130
	v_xor_b32_e32 v95, 0x80000000, v109
	v_xor_b32_e32 v94, 0x80000000, v108
	ds_write_b128 v199, v[88:91] offset:40960
	ds_write_b128 v199, v[92:95] offset:32784
	v_pk_mul_f32 v[88:89], v[120:121], v[130:131]
	v_pk_mul_f32 v[90:91], v[122:123], v[108:109]
	ds_write_b128 v199, v[88:91] offset:40976
	v_fma_f32 v88, v96, v116, 0
	v_fmac_f32_e32 v88, v97, v117
	v_fmac_f32_e32 v88, v98, v118
	v_fmac_f32_e32 v88, v99, v119
	v_fmac_f32_e32 v88, v100, v104
	v_fmac_f32_e32 v88, v101, v105
	v_fmac_f32_e32 v88, v102, v106
	v_fmac_f32_e32 v88, v103, v107
	s_nop 1
	v_add_f32_dpp v88, v88, v88 quad_perm:[1,0,3,2] row_mask:0xf bank_mask:0xf bound_ctrl:1
	s_nop 1
	v_add_f32_dpp v88, v88, v88 quad_perm:[2,3,0,1] row_mask:0xf bank_mask:0xf bound_ctrl:1
	s_nop 1
	v_mov_b32_dpp v89, v88 row_half_mirror row_mask:0xf bank_mask:0xf bound_ctrl:1
	s_and_saveexec_b64 s[14:15], s[12:13]
	s_cbranch_execz .LBB0_458
	v_lshlrev_b64 v[90:91], 6, v[128:129]
	v_lshl_add_u64 v[90:91], s[22:23], 0, v[90:91]
	v_add_f32_e32 v88, v88, v89
	global_store_dword v[90:91], v88, off
.LBB0_458:
	s_or_b64 exec, exec, s[14:15]
	s_waitcnt lgkmcnt(0)
	s_barrier
	ds_read_b128 v[104:107], v201 offset:32768
	ds_read_b128 v[112:115], v201 offset:32784
	ds_read_b128 v[88:91], v201 offset:8192
	ds_read_b128 v[96:99], v201 offset:8208
	ds_read_b128 v[92:95], v201 offset:40960
	ds_read_b128 v[100:103], v201 offset:40976
	ds_read_b128 v[108:111], v201 offset:24576
	ds_read_b128 v[116:119], v201 offset:24592
	v_add_u32_e32 v120, 0x4000, v202
	ds_read2_b32 v[130:131], v120 offset1:32
	ds_read_b128 v[120:123], v201
	ds_read_b128 v[124:127], v201 offset:16
	s_mov_b32 s14, 0
	s_waitcnt lgkmcnt(0)
	v_mov_b32_e32 v132, v131
.LBB0_459:
	v_add_u32_e32 v137, s14, v201
	v_add_u32_e32 v136, s14, v205
	v_pk_mul_f32 v[134:135], v[104:105], v[84:85]
	v_pk_mul_f32 v[104:105], v[104:105], v[76:77]
	v_pk_fma_f32 v[134:135], v[86:87], v[106:107], v[134:135]
	v_pk_fma_f32 v[104:105], v[78:79], v[106:107], v[104:105]
	v_pk_fma_f32 v[134:135], v[80:81], v[112:113], v[134:135]
	v_pk_fma_f32 v[104:105], v[72:73], v[112:113], v[104:105]
	v_pk_fma_f32 v[134:135], v[82:83], v[114:115], v[134:135]
	v_pk_fma_f32 v[138:139], v[74:75], v[114:115], v[104:105]
	ds_read_b128 v[104:107], v137 offset:33024
	ds_read_b128 v[112:115], v137 offset:33040
	v_add_f32_e32 v134, v134, v135
	v_add_f32_e32 v135, v138, v139
	v_pk_mul_f32 v[140:141], v[88:89], v[130:131] op_sel_hi:[1,0]
	v_add_f32_dpp v134, v134, v134 quad_perm:[1,0,3,2] row_mask:0xf bank_mask:0xf bound_ctrl:1
	v_add_f32_dpp v135, v135, v135 quad_perm:[1,0,3,2] row_mask:0xf bank_mask:0xf bound_ctrl:1
	v_pk_mul_f32 v[142:143], v[90:91], v[130:131] op_sel_hi:[1,0]
	v_add_f32_dpp v134, v134, v134 quad_perm:[2,3,0,1] row_mask:0xf bank_mask:0xf bound_ctrl:1
	v_add_f32_dpp v135, v135, v135 quad_perm:[2,3,0,1] row_mask:0xf bank_mask:0xf bound_ctrl:1
	v_pk_mul_f32 v[144:145], v[96:97], v[130:131] op_sel_hi:[1,0]
	v_pk_mul_f32 v[146:147], v[98:99], v[130:131] op_sel_hi:[1,0]
	v_pk_mul_f32 v[164:165], v[88:89], v[132:133] op_sel_hi:[1,0]
	v_add_f32_dpp v134, v134, v134 row_half_mirror row_mask:0xf bank_mask:0xf bound_ctrl:1
	v_add_f32_dpp v138, v135, v135 row_half_mirror row_mask:0xf bank_mask:0xf bound_ctrl:1
	v_pk_mul_f32 v[166:167], v[90:91], v[132:133] op_sel_hi:[1,0]
	v_pk_mul_f32 v[168:169], v[96:97], v[132:133] op_sel_hi:[1,0]
	v_pk_mul_f32 v[132:133], v[98:99], v[132:133] op_sel_hi:[1,0]
	ds_read_b128 v[96:99], v137 offset:8448
	ds_read_b128 v[88:91], v137 offset:8464
	ds_read2_b32 v[130:131], v136 offset1:32
	s_waitcnt lgkmcnt(11)
	v_pk_fma_f32 v[140:141], v[134:135], v[92:93], v[140:141] op_sel_hi:[0,1,1]
	v_pk_fma_f32 v[142:143], v[134:135], v[94:95], v[142:143] op_sel_hi:[0,1,1]
	v_pk_fma_f32 v[144:145], v[134:135], v[100:101], v[144:145] op_sel_hi:[0,1,1]
	v_pk_fma_f32 v[134:135], v[134:135], v[102:103], v[146:147] op_sel_hi:[0,1,1]
	v_pk_fma_f32 v[146:147], v[138:139], v[92:93], v[164:165] op_sel_hi:[0,1,1]
	v_pk_fma_f32 v[164:165], v[138:139], v[94:95], v[166:167] op_sel_hi:[0,1,1]
	v_pk_fma_f32 v[132:133], v[138:139], v[102:103], v[132:133] op_sel_hi:[0,1,1]
	s_waitcnt lgkmcnt(10)
	v_pk_fma_f32 v[84:85], v[84:85], v[108:109], v[140:141]
	v_pk_fma_f32 v[108:109], v[76:77], v[108:109], v[146:147]
	v_pk_fma_f32 v[166:167], v[138:139], v[100:101], v[168:169] op_sel_hi:[0,1,1]
	ds_read_b128 v[100:103], v137 offset:41216
	ds_read_b128 v[92:95], v137 offset:41232
	v_pk_fma_f32 v[86:87], v[86:87], v[110:111], v[142:143]
	s_waitcnt lgkmcnt(10)
	v_pk_fma_f32 v[82:83], v[82:83], v[118:119], v[134:135]
	v_pk_fma_f32 v[110:111], v[78:79], v[110:111], v[164:165]
	v_pk_fma_f32 v[118:119], v[74:75], v[118:119], v[132:133]
	v_pk_mul_f32 v[132:133], v[120:121], v[84:85]
	v_pk_mul_f32 v[120:121], v[120:121], v[108:109]
	v_pk_fma_f32 v[80:81], v[80:81], v[116:117], v[144:145]
	v_pk_fma_f32 v[116:117], v[72:73], v[116:117], v[166:167]
	v_pk_fma_f32 v[132:133], v[86:87], v[122:123], v[132:133]
	v_pk_fma_f32 v[120:121], v[110:111], v[122:123], v[120:121]
	s_waitcnt lgkmcnt(9)
	v_pk_fma_f32 v[132:133], v[80:81], v[124:125], v[132:133]
	v_pk_fma_f32 v[120:121], v[116:117], v[124:125], v[120:121]
	v_pk_fma_f32 v[132:133], v[82:83], v[126:127], v[132:133]
	v_pk_fma_f32 v[134:135], v[118:119], v[126:127], v[120:121]
	v_add_f32_e32 v132, v132, v133
	v_add_f32_e32 v133, v134, v135
	ds_read_b128 v[76:79], v137 offset:24832
	v_add_f32_dpp v132, v132, v132 quad_perm:[1,0,3,2] row_mask:0xf bank_mask:0xf bound_ctrl:1
	v_add_f32_dpp v133, v133, v133 quad_perm:[1,0,3,2] row_mask:0xf bank_mask:0xf bound_ctrl:1
	ds_read_b128 v[72:75], v137 offset:24848
	v_add_f32_dpp v132, v132, v132 quad_perm:[2,3,0,1] row_mask:0xf bank_mask:0xf bound_ctrl:1
	v_add_f32_dpp v133, v133, v133 quad_perm:[2,3,0,1] row_mask:0xf bank_mask:0xf bound_ctrl:1
	ds_read_b128 v[124:127], v137 offset:256
	v_add_f32_dpp v132, v132, v132 row_half_mirror row_mask:0xf bank_mask:0xf bound_ctrl:1
	v_add_f32_dpp v133, v133, v133 row_half_mirror row_mask:0xf bank_mask:0xf bound_ctrl:1
	ds_read_b128 v[120:123], v137 offset:272
	ds_write_b32 v136, v132 offset:32512
	ds_write_b32 v136, v133 offset:32640
	s_waitcnt lgkmcnt(12)
	v_pk_mul_f32 v[132:133], v[104:105], v[84:85]
	v_pk_mul_f32 v[104:105], v[104:105], v[108:109]
	v_pk_fma_f32 v[132:133], v[86:87], v[106:107], v[132:133]
	v_pk_fma_f32 v[104:105], v[110:111], v[106:107], v[104:105]
	s_waitcnt lgkmcnt(11)
	v_pk_fma_f32 v[132:133], v[80:81], v[112:113], v[132:133]
	v_pk_fma_f32 v[104:105], v[116:117], v[112:113], v[104:105]
	v_pk_fma_f32 v[132:133], v[82:83], v[114:115], v[132:133]
	v_pk_fma_f32 v[134:135], v[118:119], v[114:115], v[104:105]
	ds_read_b128 v[104:107], v137 offset:33280
	ds_read_b128 v[112:115], v137 offset:33296
	v_add_f32_e32 v132, v132, v133
	v_add_f32_e32 v133, v134, v135
	s_waitcnt lgkmcnt(10)
	v_pk_mul_f32 v[138:139], v[96:97], v[130:131] op_sel_hi:[1,0]
	v_add_f32_dpp v132, v132, v132 quad_perm:[1,0,3,2] row_mask:0xf bank_mask:0xf bound_ctrl:1
	v_add_f32_dpp v133, v133, v133 quad_perm:[1,0,3,2] row_mask:0xf bank_mask:0xf bound_ctrl:1
	v_pk_mul_f32 v[140:141], v[98:99], v[130:131] op_sel_hi:[1,0]
	v_pk_mul_f32 v[142:143], v[88:89], v[130:131] op_sel_hi:[1,0]
	v_pk_mul_f32 v[144:145], v[90:91], v[130:131] op_sel_hi:[1,0]
	v_mov_b32_e32 v130, v131
	v_add_f32_dpp v132, v132, v132 quad_perm:[2,3,0,1] row_mask:0xf bank_mask:0xf bound_ctrl:1
	v_add_f32_dpp v133, v133, v133 quad_perm:[2,3,0,1] row_mask:0xf bank_mask:0xf bound_ctrl:1
	v_pk_mul_f32 v[146:147], v[96:97], v[130:131] op_sel_hi:[1,0]
	v_add_f32_dpp v132, v132, v132 row_half_mirror row_mask:0xf bank_mask:0xf bound_ctrl:1
	v_add_f32_dpp v134, v133, v133 row_half_mirror row_mask:0xf bank_mask:0xf bound_ctrl:1
	v_pk_mul_f32 v[164:165], v[98:99], v[130:131] op_sel_hi:[1,0]
	s_waitcnt lgkmcnt(8)
	v_pk_fma_f32 v[138:139], v[132:133], v[100:101], v[138:139] op_sel_hi:[0,1,1]
	v_pk_fma_f32 v[140:141], v[132:133], v[102:103], v[140:141] op_sel_hi:[0,1,1]
	v_pk_fma_f32 v[142:143], v[132:133], v[92:93], v[142:143] op_sel_hi:[0,1,1]
	v_pk_fma_f32 v[132:133], v[132:133], v[94:95], v[144:145] op_sel_hi:[0,1,1]
	v_pk_fma_f32 v[144:145], v[134:135], v[100:101], v[146:147] op_sel_hi:[0,1,1]
	v_pk_mul_f32 v[166:167], v[88:89], v[130:131] op_sel_hi:[1,0]
	v_pk_fma_f32 v[146:147], v[134:135], v[102:103], v[164:165] op_sel_hi:[0,1,1]
	s_waitcnt lgkmcnt(7)
	v_pk_fma_f32 v[84:85], v[84:85], v[76:77], v[138:139]
	v_pk_fma_f32 v[76:77], v[108:109], v[76:77], v[144:145]
	v_pk_mul_f32 v[168:169], v[90:91], v[130:131] op_sel_hi:[1,0]
	ds_read_b128 v[88:91], v137 offset:8704
	ds_read_b128 v[96:99], v137 offset:8720
	ds_read2_b32 v[130:131], v136 offset0:64 offset1:96
	v_pk_fma_f32 v[164:165], v[134:135], v[92:93], v[166:167] op_sel_hi:[0,1,1]
	v_pk_fma_f32 v[86:87], v[86:87], v[78:79], v[140:141]
	s_waitcnt lgkmcnt(8)
	v_pk_fma_f32 v[82:83], v[82:83], v[74:75], v[132:133]
	v_pk_fma_f32 v[78:79], v[110:111], v[78:79], v[146:147]
	v_pk_mul_f32 v[132:133], v[124:125], v[84:85]
	v_pk_mul_f32 v[124:125], v[124:125], v[76:77]
	v_pk_fma_f32 v[134:135], v[134:135], v[94:95], v[168:169] op_sel_hi:[0,1,1]
	ds_read_b128 v[92:95], v137 offset:41472
	ds_read_b128 v[100:103], v137 offset:41488
	v_pk_fma_f32 v[80:81], v[80:81], v[72:73], v[142:143]
	v_pk_fma_f32 v[72:73], v[116:117], v[72:73], v[164:165]
	v_pk_fma_f32 v[132:133], v[86:87], v[126:127], v[132:133]
	v_pk_fma_f32 v[124:125], v[78:79], v[126:127], v[124:125]
	v_pk_fma_f32 v[74:75], v[118:119], v[74:75], v[134:135]
	s_waitcnt lgkmcnt(9)
	v_pk_fma_f32 v[132:133], v[80:81], v[120:121], v[132:133]
	v_pk_fma_f32 v[120:121], v[72:73], v[120:121], v[124:125]
	v_pk_fma_f32 v[132:133], v[82:83], v[122:123], v[132:133]
	v_pk_fma_f32 v[134:135], v[74:75], v[122:123], v[120:121]
	v_add_f32_e32 v132, v132, v133
	v_add_f32_e32 v133, v134, v135
	ds_read_b128 v[108:111], v137 offset:25088
	v_add_f32_dpp v132, v132, v132 quad_perm:[1,0,3,2] row_mask:0xf bank_mask:0xf bound_ctrl:1
	v_add_f32_dpp v133, v133, v133 quad_perm:[1,0,3,2] row_mask:0xf bank_mask:0xf bound_ctrl:1
	ds_read_b128 v[116:119], v137 offset:25104
	v_add_f32_dpp v132, v132, v132 quad_perm:[2,3,0,1] row_mask:0xf bank_mask:0xf bound_ctrl:1
	v_add_f32_dpp v133, v133, v133 quad_perm:[2,3,0,1] row_mask:0xf bank_mask:0xf bound_ctrl:1
	ds_read_b128 v[120:123], v137 offset:512
	v_add_f32_dpp v132, v132, v132 row_half_mirror row_mask:0xf bank_mask:0xf bound_ctrl:1
	v_add_f32_dpp v133, v133, v133 row_half_mirror row_mask:0xf bank_mask:0xf bound_ctrl:1
	ds_read_b128 v[124:127], v137 offset:528
	ds_write_b32 v136, v132 offset:32768
	ds_write_b32 v136, v133 offset:32896
	s_waitcnt lgkmcnt(8)
	v_mov_b32_e32 v132, v131
	s_addk_i32 s14, 0x200
	s_cmpk_eq_i32 s14, 0x2000
	s_cbranch_scc0 .LBB0_459
	s_waitcnt lgkmcnt(0)
	s_barrier
	ds_read_b128 v[88:91], v199 offset:49152
	ds_read_b128 v[92:95], v199 offset:49168
	s_cmp_eq_u32 s2, 8
	s_waitcnt lgkmcnt(1)
	v_cvt_pk_bf16_f32 v88, v88, v89
	v_cvt_pk_bf16_f32 v89, v90, v91
	s_waitcnt lgkmcnt(0)
	v_cvt_pk_bf16_f32 v90, v92, v93
	v_lshlrev_b64 v[92:93], 10, v[128:129]
	v_cvt_pk_bf16_f32 v91, v94, v95
	v_lshl_add_u64 v[92:93], v[154:155], 0, v[92:93]
	global_store_dwordx4 v[92:93], v[88:91], off
	s_cbranch_scc1 .LBB0_463
	v_mov_b64_e32 v[106:107], v[70:71]
	v_mov_b64_e32 v[90:91], v[54:55]
	v_mov_b64_e32 v[94:95], v[58:59]
	v_mov_b64_e32 v[110:111], v[62:63]
	v_mov_b64_e32 v[114:115], v[66:67]
	v_mov_b64_e32 v[104:105], v[68:69]
	v_mov_b64_e32 v[88:89], v[52:53]
	v_mov_b64_e32 v[92:93], v[56:57]
	v_mov_b64_e32 v[108:109], v[60:61]
	v_mov_b64_e32 v[112:113], v[64:65]
	s_mov_b32 s14, s2
	s_branch .LBB0_447

.LBB0_480:
	s_or_b64 exec, exec, s[16:17]
	s_lshl_b32 s15, s2, 16
	s_add_u32 s16, s92, s15
	s_addc_u32 s17, s93, 0
	v_lshlrev_b64 v[4:5], 7, v[148:149]
	v_lshl_add_u64 v[6:7], s[16:17], 0, v[4:5]
	s_add_u32 s16, s83, s15
	s_addc_u32 s17, s94, 0
	v_lshl_add_u64 v[4:5], s[16:17], 0, v[4:5]
	s_lshl_b64 s[16:17], s[26:27], 11
	s_waitcnt lgkmcnt(0)
	s_add_u32 s12, s12, s16
	s_addc_u32 s13, s13, s17
	s_add_u32 s22, s22, s16
	v_mov_b64_e32 v[8:9], s[44:45]
	s_addc_u32 s23, s23, s17
	v_mad_u64_u32 v[10:11], s[16:17], v2, s43, v[8:9]
	v_and_b32_e32 v73, 7, v68
	v_mad_i32_i24 v11, v3, s43, v11
	v_lshlrev_b64 v[76:77], 1, v[148:149]
	v_lshlrev_b64 v[2:3], 9, v[2:3]
	v_lshlrev_b64 v[74:75], 2, v[148:149]
	v_lshl_add_u64 v[10:11], v[10:11], 0, v[76:77]
	v_lshlrev_b32_e32 v148, 4, v73
	v_lshl_add_u64 v[2:3], s[40:41], 0, v[2:3]
	s_lshl_b32 s26, s2, 8
	v_lshl_add_u64 v[10:11], v[10:11], 0, v[148:149]
	v_lshl_add_u64 v[2:3], v[2:3], 0, s[26:27]
	v_mad_u64_u32 v[8:9], s[16:17], v0, s43, v[8:9]
	global_load_dwordx4 v[104:107], v[10:11], off
	global_load_dwordx4 v[88:91], v[10:11], off offset:1024
	v_lshl_add_u64 v[2:3], v[2:3], 0, v[148:149]
	global_load_dwordx4 v[96:99], v[10:11], off offset:2048
	global_load_dwordx4 v[108:111], v[2:3], off
	v_mov_b32_e32 v10, v9
	v_mad_u64_u32 v[10:11], s[16:17], v1, s43, v[10:11]
	v_bfe_u32 v71, v68, 4, 2
	v_mov_b32_e32 v9, v10
	v_lshl_add_u64 v[8:9], v[8:9], 0, v[76:77]
	v_lshlrev_b64 v[0:1], 9, v[0:1]
	v_lshlrev_b32_e32 v78, 4, v71
	v_mov_b32_e32 v79, v149
	v_and_b32_e32 v69, 15, v68
	v_lshl_add_u64 v[8:9], v[8:9], 0, v[148:149]
	global_load_dwordx4 v[112:115], v[2:3], off offset:128
	global_load_dwordx4 v[48:51], v[8:9], off
	global_load_dwordx4 v[52:55], v[8:9], off offset:1024
	global_load_dwordx4 v[56:59], v[8:9], off offset:2048
	v_lshl_add_u64 v[0:1], s[40:41], 0, v[0:1]
	v_lshl_add_u64 v[2:3], v[4:5], 0, v[78:79]
	v_ashrrev_i32_e32 v4, 2, v68
	s_movk_i32 s15, 0xffe0
	v_lshl_add_u64 v[0:1], v[0:1], 0, s[26:27]
	v_and_or_b32 v80, v4, s15, v69
	v_lshl_add_u64 v[0:1], v[0:1], 0, v[148:149]
	v_ashrrev_i32_e32 v81, 31, v80
	v_or_b32_e32 v82, 16, v80
	global_load_dwordx4 v[60:63], v[0:1], off
	global_load_dwordx4 v[64:67], v[0:1], off offset:128
	v_lshl_add_u64 v[0:1], v[6:7], 0, v[78:79]
	v_lshlrev_b64 v[4:5], 7, v[80:81]
	v_ashrrev_i32_e32 v83, 31, v82
	v_lshl_add_u64 v[6:7], v[0:1], 0, v[4:5]
	v_lshl_add_u64 v[12:13], v[2:3], 0, v[4:5]
	v_lshlrev_b64 v[4:5], 7, v[82:83]
	v_lshl_add_u64 v[20:21], v[0:1], 0, v[4:5]
	v_lshl_add_u64 v[28:29], v[2:3], 0, v[4:5]
	global_load_dwordx4 v[0:3], v[6:7], off
	s_nop 0
	global_load_dwordx4 v[4:7], v[6:7], off offset:64
	s_nop 0
	global_load_dwordx4 v[8:11], v[12:13], off
	s_nop 0
	global_load_dwordx4 v[12:15], v[12:13], off offset:64
	s_nop 0
	global_load_dwordx4 v[16:19], v[20:21], off
	s_nop 0
	global_load_dwordx4 v[20:23], v[20:21], off offset:64
	s_nop 0
	global_load_dwordx4 v[24:27], v[28:29], off
	s_nop 0
	global_load_dwordx4 v[28:31], v[28:29], off offset:64
	v_lshl_add_u64 v[84:85], s[12:13], 0, v[74:75]
	s_movk_i32 s12, 0x70
	v_lshlrev_b32_e32 v79, 5, v73
	v_mul_lo_u32 v83, v192, s98
	v_mul_lo_u32 v86, v192, s12
	v_or_b32_e32 v193, 0x10400, v79
	v_add3_u32 v195, v83, v86, v79
	v_lshrrev_b32_e32 v79, 2, v68
	s_add_u32 s16, s40, s26
	v_and_b32_e32 v79, 16, v79
	v_lshl_add_u64 v[74:75], s[22:23], 0, v[74:75]
	s_addc_u32 s17, s41, 0
	v_or_b32_e32 v69, v79, v69
	s_mul_i32 s22, s2, 0x1800000
	v_mul_u32_u24_e32 v69, 0x48, v69
	s_add_u32 s22, s89, s22
	v_lshl_add_u32 v196, v69, 1, v78
	s_addc_u32 s23, s99, 0
	s_lshl_b32 s14, s14, 3
	v_lshlrev_b32_e32 v69, 6, v79
	v_cmp_eq_u32_e64 s[12:13], 0, v73
	v_lshlrev_b32_e32 v197, 2, v72
	v_lshl_add_u64 v[72:73], s[22:23], 0, v[76:77]
	s_add_u32 s14, s96, s14
	v_lshl_or_b32 v69, v71, 8, v69
	v_lshl_add_u64 v[150:151], v[72:73], 0, v[148:149]
	s_addc_u32 s23, s97, 0
	s_lshl_b32 s2, s2, 2
	v_lshlrev_b64 v[72:73], 2, v[80:81]
	v_add_lshl_u32 v199, v69, v80, 2
	v_add_lshl_u32 v200, v69, v82, 2
	v_lshlrev_b32_e32 v68, 5, v68
	v_lshlrev_b32_e32 v69, 8, v70
	v_lshlrev_b32_e32 v198, 2, v70
	s_add_u32 s22, s14, s2
	v_lshl_add_u64 v[152:153], v[84:85], 0, v[72:73]
	v_lshl_add_u64 v[154:155], v[74:75], 0, v[72:73]
	v_lshl_add_u64 v[72:73], s[44:45], 0, v[76:77]
	v_sub_u32_e32 v68, v68, v69
	v_mov_b32_e32 v223, 1
	v_mov_b32_e32 v222, 0x11ff0
	v_add_u32_e32 v194, v83, v148
	s_mov_b32 s15, 0
	s_addc_u32 s23, s23, 0
	v_lshl_add_u64 v[156:157], v[72:73], 0, v[148:149]
	v_lshl_add_u64 v[158:159], s[16:17], 0, v[148:149]
	v_add_u32_e32 v148, 0x4100, v198
	v_add_u32_e32 v201, 0x100, v68
	global_load_dword v240, v[152:153], off
	global_load_dword v241, v[154:155], off
	global_load_dword v242, v[152:153], off offset:64
	global_load_dword v243, v[154:155], off offset:64
	s_waitcnt vmcnt(0)
.LBB0_481:
	v_lshl_add_u32 v202, s15, 5, v192
	v_cmp_gt_i32_e32 vcc, 1, v202
	s_waitcnt vmcnt(2)
	v_and_b32_e32 v181, 0xffff0000, v48
	v_lshlrev_b32_e32 v180, 16, v48
	v_and_b32_e32 v177, 0xffff0000, v49
	v_lshlrev_b32_e32 v176, 16, v49
	v_and_b32_e32 v173, 0xffff0000, v50
	v_lshlrev_b32_e32 v172, 16, v50
	v_and_b32_e32 v169, 0xffff0000, v51
	v_lshlrev_b32_e32 v168, 16, v51
	s_waitcnt vmcnt(11)
	v_and_b32_e32 v161, 0xffff0000, v52
	v_lshlrev_b32_e32 v160, 16, v52
	v_and_b32_e32 v163, 0xffff0000, v53
	v_lshlrev_b32_e32 v162, 16, v53
	v_and_b32_e32 v165, 0xffff0000, v54
	v_lshlrev_b32_e32 v164, 16, v54
	v_and_b32_e32 v167, 0xffff0000, v55
	v_lshlrev_b32_e32 v166, 16, v55
	s_waitcnt vmcnt(10)
	v_and_b32_e32 v187, 0xffff0000, v56
	v_lshlrev_b32_e32 v186, 16, v56
	v_and_b32_e32 v183, 0xffff0000, v57
	v_lshlrev_b32_e32 v182, 16, v57
	v_and_b32_e32 v175, 0xffff0000, v58
	v_lshlrev_b32_e32 v174, 16, v58
	v_and_b32_e32 v171, 0xffff0000, v59
	v_lshlrev_b32_e32 v170, 16, v59
	s_waitcnt vmcnt(9)
	v_and_b32_e32 v209, 0xffff0000, v60
	v_lshlrev_b32_e32 v210, 16, v60
	v_and_b32_e32 v207, 0xffff0000, v61
	v_lshlrev_b32_e32 v208, 16, v61
	v_and_b32_e32 v205, 0xffff0000, v62
	v_lshlrev_b32_e32 v206, 16, v62
	v_and_b32_e32 v203, 0xffff0000, v63
	v_lshlrev_b32_e32 v204, 16, v63
	s_waitcnt vmcnt(8)
	v_and_b32_e32 v191, 0xffff0000, v64
	v_lshlrev_b32_e32 v190, 16, v64
	v_and_b32_e32 v189, 0xffff0000, v65
	v_lshlrev_b32_e32 v188, 16, v65
	v_and_b32_e32 v185, 0xffff0000, v66
	v_lshlrev_b32_e32 v184, 16, v66
	v_and_b32_e32 v179, 0xffff0000, v67
	v_lshlrev_b32_e32 v178, 16, v67
	s_and_saveexec_b64 s[36:37], vcc
	s_cbranch_execz .LBB0_483
	v_mov_b32_e32 v180, 0
	v_mov_b32_e32 v181, v180
	v_mov_b32_e32 v176, v180
	v_mov_b32_e32 v177, v180
	v_mov_b32_e32 v172, v180
	v_mov_b32_e32 v173, v180
	v_mov_b32_e32 v168, v180
	v_mov_b32_e32 v169, v180
	v_mov_b32_e32 v186, v180
	v_mov_b32_e32 v187, v180
	v_mov_b32_e32 v182, v180
	v_mov_b32_e32 v183, v180
	v_mov_b32_e32 v174, v180
	v_mov_b32_e32 v175, v180
	v_mov_b32_e32 v170, v180
	v_mov_b32_e32 v171, v180
	v_mov_b32_e32 v160, v180
	v_mov_b32_e32 v161, v180
	v_mov_b32_e32 v162, v180
	v_mov_b32_e32 v163, v180
	v_mov_b32_e32 v164, v180
	v_mov_b32_e32 v165, v180
	v_mov_b32_e32 v166, v180
	v_mov_b32_e32 v167, v180
	v_mov_b32_e32 v178, v180
	v_mov_b32_e32 v179, v180
	v_mov_b32_e32 v184, v180
	v_mov_b32_e32 v185, v180
	v_mov_b32_e32 v188, v180
	v_mov_b32_e32 v189, v180
	v_mov_b32_e32 v190, v180
	v_mov_b32_e32 v191, v180
	v_mov_b32_e32 v210, v180
	v_mov_b32_e32 v209, v180
	v_mov_b32_e32 v208, v180
	v_mov_b32_e32 v207, v180
	v_mov_b32_e32 v206, v180
	v_mov_b32_e32 v205, v180
	v_mov_b32_e32 v204, v180
	v_mov_b32_e32 v203, v180

.LBB0_490:
	v_lshlrev_b32_e32 v211, 16, v108
	v_and_b32_e32 v226, 0xffff0000, v108
	v_lshlrev_b32_e32 v227, 16, v109
	v_and_b32_e32 v228, 0xffff0000, v109
	v_lshlrev_b32_e32 v229, 16, v110
	v_and_b32_e32 v230, 0xffff0000, v110
	v_lshlrev_b32_e32 v231, 16, v111
	v_and_b32_e32 v232, 0xffff0000, v111
	v_and_b32_e32 v111, 0xffff0000, v112
	v_lshlrev_b32_e32 v110, 16, v112
	v_and_b32_e32 v213, 0xffff0000, v113
	v_lshlrev_b32_e32 v212, 16, v113
	v_and_b32_e32 v215, 0xffff0000, v114
	v_lshlrev_b32_e32 v214, 16, v114
	v_and_b32_e32 v217, 0xffff0000, v115
	v_lshlrev_b32_e32 v216, 16, v115
	v_and_b32_e32 v109, 0xffff0000, v104
	v_lshlrev_b32_e32 v108, 16, v104
	v_and_b32_e32 v113, 0xffff0000, v105
	v_lshlrev_b32_e32 v112, 16, v105
	v_and_b32_e32 v105, 0xffff0000, v106
	v_lshlrev_b32_e32 v104, 16, v106
	v_and_b32_e32 v115, 0xffff0000, v107
	v_lshlrev_b32_e32 v114, 16, v107
	v_and_b32_e32 v107, 0xffff0000, v96
	v_lshlrev_b32_e32 v106, 16, v96
	v_sub_f32_e32 v96, v210, v211
	v_and_b32_e32 v219, 0xffff0000, v97
	v_lshlrev_b32_e32 v218, 16, v97
	v_and_b32_e32 v221, 0xffff0000, v98
	v_lshlrev_b32_e32 v220, 16, v98
	v_and_b32_e32 v225, 0xffff0000, v99
	v_lshlrev_b32_e32 v224, 16, v99
	s_waitcnt lgkmcnt(7)
	v_fmac_f32_e32 v211, v96, v132
	v_pk_add_f32 v[96:97], v[180:181], v[108:109] neg_lo:[0,1] neg_hi:[0,1]
	v_pk_add_f32 v[98:99], v[186:187], v[106:107] neg_lo:[0,1] neg_hi:[0,1]
	v_pk_fma_f32 v[96:97], v[96:97], v[136:137], v[108:109]
	s_waitcnt lgkmcnt(3)
	v_pk_fma_f32 v[108:109], v[98:99], v[144:145], v[106:107]
	v_sub_f32_e32 v98, v209, v226
	v_fmac_f32_e32 v226, v98, v133
	v_pk_add_f32 v[98:99], v[190:191], v[110:111] neg_lo:[0,1] neg_hi:[0,1]
	v_pk_add_f32 v[106:107], v[182:183], v[218:219] neg_lo:[0,1] neg_hi:[0,1]
	s_waitcnt lgkmcnt(1)
	v_pk_fma_f32 v[132:133], v[98:99], v[140:141], v[110:111]
	v_pk_fma_f32 v[110:111], v[106:107], v[146:147], v[218:219]
	v_sub_f32_e32 v106, v207, v228
	v_sub_f32_e32 v98, v208, v227
	v_fmac_f32_e32 v228, v106, v135
	v_pk_add_f32 v[106:107], v[188:189], v[212:213] neg_lo:[0,1] neg_hi:[0,1]
	v_fmac_f32_e32 v227, v98, v134
	v_pk_fma_f32 v[134:135], v[106:107], v[142:143], v[212:213]
	v_sub_f32_e32 v106, v206, v229
	v_fmac_f32_e32 v229, v106, v120
	v_pk_add_f32 v[106:107], v[172:173], v[104:105] neg_lo:[0,1] neg_hi:[0,1]
	v_pk_add_f32 v[98:99], v[176:177], v[112:113] neg_lo:[0,1] neg_hi:[0,1]
	v_pk_fma_f32 v[104:105], v[106:107], v[124:125], v[104:105]
	v_pk_add_f32 v[106:107], v[174:175], v[220:221] neg_lo:[0,1] neg_hi:[0,1]
	v_pk_fma_f32 v[98:99], v[98:99], v[138:139], v[112:113]
	v_pk_fma_f32 v[112:113], v[106:107], v[128:129], v[220:221]
	v_sub_f32_e32 v106, v205, v230
	v_fmac_f32_e32 v230, v106, v121
	v_pk_add_f32 v[106:107], v[184:185], v[214:215] neg_lo:[0,1] neg_hi:[0,1]
	v_and_b32_e32 v137, 0xffff0000, v90
	s_waitcnt lgkmcnt(0)
	v_pk_fma_f32 v[120:121], v[106:107], v[116:117], v[214:215]
	v_sub_f32_e32 v106, v204, v231
	v_fmac_f32_e32 v231, v106, v122
	v_add_f32_e32 v122, v211, v211
	v_mul_f32_e32 v122, 0x3fb8aa3b, v122
	v_exp_f32_e32 v124, v122
	v_add_f32_e32 v122, v226, v226
	v_mul_f32_e32 v122, 0x3fb8aa3b, v122
	v_exp_f32_e32 v125, v122
	v_sub_f32_e32 v116, v203, v232
	v_pk_add_f32 v[106:107], v[168:169], v[114:115] neg_lo:[0,1] neg_hi:[0,1]
	v_fmac_f32_e32 v232, v116, v123
	v_pk_add_f32 v[116:117], v[178:179], v[216:217] neg_lo:[0,1] neg_hi:[0,1]
	v_pk_fma_f32 v[106:107], v[106:107], v[126:127], v[114:115]
	v_pk_fma_f32 v[122:123], v[116:117], v[118:119], v[216:217]
	v_add_f32_e32 v116, 1.0, v124
	v_add_f32_e32 v117, 1.0, v125
	v_add_f32_e32 v118, v227, v227
	v_add_f32_e32 v119, v228, v228
	v_add_f32_e32 v124, v229, v229
	v_add_f32_e32 v125, v230, v230
	v_add_f32_e32 v126, v231, v231
	v_add_f32_e32 v127, v232, v232
	v_mul_f32_e32 v118, 0x3fb8aa3b, v118
	v_mul_f32_e32 v119, 0x3fb8aa3b, v119
	v_mul_f32_e32 v124, 0x3fb8aa3b, v124
	v_mul_f32_e32 v125, 0x3fb8aa3b, v125
	v_mul_f32_e32 v126, 0x3fb8aa3b, v126
	v_mul_f32_e32 v127, 0x3fb8aa3b, v127
	v_exp_f32_e32 v118, v118
	v_exp_f32_e32 v119, v119
	v_exp_f32_e32 v124, v124
	v_exp_f32_e32 v125, v125
	v_exp_f32_e32 v126, v126
	v_exp_f32_e32 v127, v127
	v_add_f32_e32 v118, 1.0, v118
	v_add_f32_e32 v119, 1.0, v119
	v_add_f32_e32 v124, 1.0, v124
	v_add_f32_e32 v125, 1.0, v125
	v_add_f32_e32 v126, 1.0, v126
	v_add_f32_e32 v127, 1.0, v127
	v_rcp_f32_e32 v116, v116
	v_rcp_f32_e32 v117, v117
	v_rcp_f32_e32 v118, v118
	v_rcp_f32_e32 v119, v119
	v_rcp_f32_e32 v124, v124
	v_rcp_f32_e32 v125, v125
	v_rcp_f32_e32 v126, v126
	v_rcp_f32_e32 v127, v127
	v_pk_fma_f32 v[116:117], v[116:117], 2.0, 1.0 op_sel_hi:[1,0,0] neg_lo:[1,0,0] neg_hi:[1,0,0]
	v_pk_fma_f32 v[118:119], v[118:119], 2.0, 1.0 op_sel_hi:[1,0,0] neg_lo:[1,0,0] neg_hi:[1,0,0]
	v_pk_fma_f32 v[124:125], v[124:125], 2.0, 1.0 op_sel_hi:[1,0,0] neg_lo:[1,0,0] neg_hi:[1,0,0]
	v_pk_fma_f32 v[126:127], v[126:127], 2.0, 1.0 op_sel_hi:[1,0,0] neg_lo:[1,0,0] neg_hi:[1,0,0]
	v_cvt_pk_bf16_f32 v116, v116, v117
	v_cvt_pk_bf16_f32 v117, v118, v119
	v_cvt_pk_bf16_f32 v118, v124, v125
	v_cvt_pk_bf16_f32 v119, v126, v127
	v_pk_add_f32 v[114:115], v[170:171], v[224:225] neg_lo:[0,1] neg_hi:[0,1]
	ds_write_b128 v194, v[116:119] offset:57344
	v_cvt_pk_bf16_f32 v116, v132, v133
	v_cvt_pk_bf16_f32 v117, v134, v135
	v_cvt_pk_bf16_f32 v118, v120, v121
	v_cvt_pk_bf16_f32 v119, v122, v123
	v_pk_fma_f32 v[114:115], v[114:115], v[130:131], v[224:225]
	ds_write_b128 v194, v[116:119] offset:61952
	ds_write_b128 v195, v[96:99]
	ds_write_b128 v195, v[108:111] offset:16384
	ds_write_b128 v195, v[104:107] offset:16
	ds_write_b128 v195, v[112:115] offset:16400
	s_waitcnt lgkmcnt(0)
	s_barrier
	ds_read_b128 v[108:111], v196 offset:57344
	ds_read_b128 v[116:119], v196 offset:57408
	ds_read_b128 v[112:115], v196 offset:61952
	ds_read_b128 v[124:127], v196 offset:62016
	s_waitcnt lgkmcnt(3)
	v_mfma_f32_16x16x32_bf16 v[120:123], v[108:111], v[0:3], 0
	v_and_b32_e32 v133, 0xffff0000, v88
	v_lshlrev_b32_e32 v132, 16, v88
	v_and_b32_e32 v135, 0xffff0000, v89
	v_lshlrev_b32_e32 v134, 16, v89
	v_lshlrev_b32_e32 v136, 16, v90
	v_and_b32_e32 v139, 0xffff0000, v91
	v_lshlrev_b32_e32 v138, 16, v91
	s_nop 0
	v_mfma_f32_16x16x32_bf16 v[88:91], v[108:111], v[16:19], 0
	v_add_f32_e64 v108, v160, -v132
	v_add_f32_e64 v109, v161, -v133
	v_pk_fma_f32 v[132:133], v[108:109], v[100:101], v[132:133]
	v_pk_add_f32 v[100:101], v[162:163], v[134:135] neg_lo:[0,1] neg_hi:[0,1]
	s_waitcnt lgkmcnt(1)
	v_mfma_f32_16x16x32_bf16 v[128:131], v[112:115], v[8:11], 0
	v_fma_f32 v134, v100, v102, v134
	v_fma_f32 v135, v101, v103, v135
	v_mfma_f32_16x16x32_bf16 v[100:103], v[116:119], v[4:7], v[120:123]
	s_nop 0
	v_mfma_f32_16x16x32_bf16 v[108:111], v[112:115], v[24:27], 0
	v_add_f32_e64 v112, v164, -v136
	v_add_f32_e64 v113, v165, -v137
	s_nop 0
	s_nop 2
	v_add_f32_e32 v101, v101, v240
	v_add_f32_e32 v102, v102, v240
	v_mfma_f32_16x16x32_bf16 v[88:91], v[116:119], v[20:23], v[88:91]
	v_mul_f32_e32 v101, 0xbfb8aa3b, v101
	v_mul_f32_e32 v102, 0xbfb8aa3b, v102
	v_add_f32_e32 v103, v103, v240
	v_pk_fma_f32 v[136:137], v[112:113], v[92:93], v[136:137]
	v_pk_add_f32 v[92:93], v[166:167], v[138:139] neg_lo:[0,1] neg_hi:[0,1]
	v_exp_f32_e32 v101, v101
	v_exp_f32_e32 v102, v102
	v_mul_f32_e32 v103, 0xbfb8aa3b, v103
	v_pk_fma_f32 v[138:139], v[92:93], v[94:95], v[138:139]
	s_waitcnt lgkmcnt(0)
	v_mfma_f32_16x16x32_bf16 v[92:95], v[124:127], v[12:15], v[128:131]
	v_exp_f32_e32 v103, v103
	v_add_f32_e32 v100, v100, v240
	s_nop 0
	v_add_f32_e32 v88, v88, v242
	v_mul_f32_e32 v100, 0xbfb8aa3b, v100
	v_add_f32_e32 v101, 1.0, v101
	v_add_f32_e32 v102, 1.0, v102
	v_mul_f32_e32 v88, 0xbfb8aa3b, v88
	v_exp_f32_e32 v100, v100
	v_add_f32_e32 v92, v92, v241
	v_rcp_f32_e32 v101, v101
	v_rcp_f32_e32 v102, v102
	v_add_f32_e32 v103, 1.0, v103
	v_exp_f32_e32 v88, v88
	v_mul_f32_e32 v92, 0xbfb8aa3b, v92
	v_add_f32_e32 v94, v94, v241
	v_rcp_f32_e32 v103, v103
	v_add_f32_e32 v95, v95, v241
	v_exp_f32_e32 v92, v92
	v_mul_f32_e32 v94, 0xbfb8aa3b, v94
	v_mul_f32_e32 v95, 0xbfb8aa3b, v95
	v_exp_f32_e32 v94, v94
	v_exp_f32_e32 v95, v95
	v_add_f32_e32 v100, 1.0, v100
	v_mul_f32_e32 v101, 0xbf1b4598, v101
	v_mul_f32_e32 v102, 0xbf1b4598, v102
	v_add_f32_e32 v88, 1.0, v88
	v_rcp_f32_e32 v100, v100
	v_mul_f32_e32 v101, 0x3fb8aa3b, v101
	v_mul_f32_e32 v102, 0x3fb8aa3b, v102
	v_mul_f32_e32 v103, 0xbf1b4598, v103
	v_rcp_f32_e32 v88, v88
	v_mfma_f32_16x16x32_bf16 v[108:111], v[124:127], v[28:31], v[108:111]
	v_add_f32_e32 v92, 1.0, v92
	v_exp_f32_e32 v101, v101
	v_exp_f32_e32 v102, v102
	v_mul_f32_e32 v103, 0x3fb8aa3b, v103
	v_rcp_f32_e32 v92, v92
	v_add_f32_e32 v94, 1.0, v94
	v_exp_f32_e32 v103, v103
	v_add_f32_e32 v95, 1.0, v95
	v_rcp_f32_e32 v94, v94
	v_rcp_f32_e32 v95, v95
	v_mul_f32_e32 v100, 0xbf1b4598, v100
	v_mul_f32_e32 v88, 0xbf1b4598, v88
	v_add_f32_e32 v89, v89, v242
	v_add_f32_e32 v90, v90, v242
	v_mul_f32_e32 v100, 0x3fb8aa3b, v100
	ds_write2st64_b32 v199, v101, v102 offset0:97 offset1:98
	ds_write2st64_b32 v199, v103, v92 offset0:99 offset1:128
	ds_write2st64_b32 v199, v94, v95 offset0:130 offset1:131
	v_mul_f32_e32 v88, 0x3fb8aa3b, v88
	s_nop 0
	v_add_f32_e32 v94, v108, v243
	v_mul_f32_e32 v89, 0xbfb8aa3b, v89
	v_mul_f32_e32 v90, 0xbfb8aa3b, v90
	v_add_f32_e32 v91, v91, v242
	v_exp_f32_e32 v100, v100
	v_exp_f32_e32 v88, v88
	v_exp_f32_e32 v89, v89
	v_mul_f32_e32 v94, 0xbfb8aa3b, v94
	v_exp_f32_e32 v90, v90
	v_mul_f32_e32 v91, 0xbfb8aa3b, v91
	v_exp_f32_e32 v94, v94
	v_exp_f32_e32 v91, v91
	v_add_f32_e32 v93, v93, v241
	v_add_u32_e32 v92, 0x6000, v199
	v_mul_f32_e32 v93, 0xbfb8aa3b, v93
	ds_write2_b32 v92, v100, v88 offset1:16
	v_add_f32_e32 v88, 1.0, v89
	v_add_f32_e32 v90, 1.0, v90
	v_exp_f32_e32 v93, v93
	v_rcp_f32_e32 v88, v88
	v_add_f32_e32 v89, 1.0, v94
	v_add_f32_e32 v94, v109, v243
	v_rcp_f32_e32 v90, v90
	v_add_f32_e32 v91, 1.0, v91
	v_mul_f32_e32 v94, 0xbfb8aa3b, v94
	v_add_f32_e32 v95, v110, v243
	v_rcp_f32_e32 v91, v91
	v_add_f32_e32 v100, v111, v243
	v_exp_f32_e32 v94, v94
	v_mul_f32_e32 v95, 0xbfb8aa3b, v95
	v_mul_f32_e32 v100, 0xbfb8aa3b, v100
	v_exp_f32_e32 v95, v95
	v_exp_f32_e32 v100, v100
	v_add_f32_e32 v93, 1.0, v93
	v_mul_f32_e32 v88, 0xbf1b4598, v88
	v_mul_f32_e32 v90, 0xbf1b4598, v90
	v_rcp_f32_e32 v93, v93
	v_rcp_f32_e32 v89, v89
	v_mul_f32_e32 v88, 0x3fb8aa3b, v88
	v_mul_f32_e32 v90, 0x3fb8aa3b, v90
	v_mul_f32_e32 v91, 0xbf1b4598, v91
	v_sub_u32_e32 v112, 0x7ff, v202
	v_exp_f32_e32 v88, v88
	v_add_f32_e32 v94, 1.0, v94
	v_exp_f32_e32 v90, v90
	v_mul_f32_e32 v91, 0x3fb8aa3b, v91
	v_cndmask_b32_e64 v112, v112, v202, s[8:9]
	v_rcp_f32_e32 v94, v94
	v_add_f32_e32 v95, 1.0, v95
	v_exp_f32_e32 v91, v91
	v_add_f32_e32 v100, 1.0, v100
	v_ashrrev_i32_e32 v113, 31, v112
	v_add_u32_e32 v92, 0x8000, v199
	v_rcp_f32_e32 v95, v95
	v_rcp_f32_e32 v100, v100
	v_lshl_add_u64 v[128:129], v[112:113], 0, s[20:21]
	ds_write2_b32 v92, v89, v93 offset0:16 offset1:64
	ds_write2st64_b32 v200, v88, v90 offset0:97 offset1:98
	ds_write2st64_b32 v200, v91, v94 offset0:99 offset1:129
	ds_write2st64_b32 v200, v95, v100 offset0:130 offset1:131
	s_waitcnt lgkmcnt(0)
	s_barrier
	ds_read_b128 v[88:91], v193 offset:1280
	ds_read_b128 v[92:95], v193 offset:1792
	ds_read_b128 v[100:103], v193 offset:1808
	ds_read_b128 v[108:111], v193 offset:1296
	ds_read_b128 v[112:115], v195 offset:32768
	ds_read_b128 v[116:119], v193 offset:1536
	ds_read_b128 v[124:127], v193 offset:1552
	s_waitcnt lgkmcnt(6)
	v_pk_mul_f32 v[130:131], v[132:133], v[88:89]
	ds_read_b128 v[120:123], v195 offset:32784
	s_waitcnt lgkmcnt(3)
	v_pk_add_f32 v[88:89], v[112:113], -1.0 op_sel_hi:[1,0]
	v_pk_mul_f32 v[140:141], v[130:131], v[130:131]
	s_waitcnt lgkmcnt(2)
	v_pk_fma_f32 v[88:89], v[88:89], v[116:117], 1.0 op_sel_hi:[1,1,0]
	s_nop 0
	v_pk_mul_f32 v[88:89], v[132:133], v[88:89]
	s_nop 0
	v_pk_mul_f32 v[116:117], v[96:97], v[88:89]
	v_pk_mul_f32 v[96:97], v[134:135], v[90:91]
	v_pk_add_f32 v[90:91], v[114:115], -1.0 op_sel_hi:[1,0]
	v_pk_mul_f32 v[132:133], v[96:97], v[96:97]
	v_pk_fma_f32 v[90:91], v[90:91], v[118:119], 1.0 op_sel_hi:[1,1,0]
	s_nop 0
	v_pk_mul_f32 v[90:91], v[134:135], v[90:91]
	ds_write_b128 v195, v[88:91] offset:8192
	s_waitcnt lgkmcnt(1)
	v_pk_add_f32 v[88:89], v[120:121], -1.0 op_sel_hi:[1,0]
	v_pk_mul_f32 v[118:119], v[98:99], v[90:91]
	v_pk_fma_f32 v[88:89], v[88:89], v[124:125], 1.0 op_sel_hi:[1,1,0]
	v_pk_add_f32 v[124:125], v[122:123], -1.0 op_sel_hi:[1,0]
	v_pk_mul_f32 v[98:99], v[136:137], v[108:109]
	v_pk_fma_f32 v[124:125], v[124:125], v[126:127], 1.0 op_sel_hi:[1,1,0]
	v_add_f32_e32 v126, v140, v141
	v_add_f32_e32 v126, v126, v132
	v_pk_mul_f32 v[90:91], v[98:99], v[98:99]
	v_add_f32_e32 v126, v126, v133
	v_pk_mul_f32 v[108:109], v[138:139], v[110:111]
	v_add_f32_e32 v90, v126, v90
	v_pk_mul_f32 v[110:111], v[108:109], v[108:109]
	v_add_f32_e32 v90, v90, v91
	v_add_f32_e32 v90, v90, v110
	v_add_f32_e32 v90, v90, v111
	v_pk_mul_f32 v[88:89], v[136:137], v[88:89]
	s_nop 0
	v_add_f32_dpp v90, v90, v90 quad_perm:[1,0,3,2] row_mask:0xf bank_mask:0xf bound_ctrl:1
	v_pk_mul_f32 v[104:105], v[104:105], v[88:89]
	s_nop 0
	v_add_f32_dpp v90, v90, v90 quad_perm:[2,3,0,1] row_mask:0xf bank_mask:0xf bound_ctrl:1
	s_nop 1
	v_add_f32_dpp v90, v90, v90 row_half_mirror row_mask:0xf bank_mask:0xf bound_ctrl:1
	v_max_f32_e32 v90, 0x179abe15, v90
	v_rsq_f32_e32 v110, v90
	v_pk_mul_f32 v[90:91], v[138:139], v[124:125]
	ds_write_b128 v195, v[88:91] offset:8208
	v_pk_mul_f32 v[106:107], v[106:107], v[90:91]
	v_pk_mul_f32 v[124:125], v[130:131], v[110:111] op_sel_hi:[1,0]
	v_pk_mul_f32 v[126:127], v[96:97], v[110:111] op_sel_hi:[1,0]
	v_xor_b32_e32 v89, 0x80000000, v125
	v_xor_b32_e32 v88, 0x80000000, v124
	v_xor_b32_e32 v91, 0x80000000, v127
	v_xor_b32_e32 v90, 0x80000000, v126
	v_pk_mul_f32 v[130:131], v[98:99], v[110:111] op_sel_hi:[1,0]
	v_pk_mul_f32 v[108:109], v[108:109], v[110:111] op_sel_hi:[1,0]
	ds_write_b128 v195, v[88:91] offset:32768
	v_pk_mul_f32 v[88:89], v[112:113], v[124:125]
	v_pk_mul_f32 v[90:91], v[114:115], v[126:127]
	v_xor_b32_e32 v97, 0x80000000, v131
	v_xor_b32_e32 v96, 0x80000000, v130
	v_xor_b32_e32 v99, 0x80000000, v109
	v_xor_b32_e32 v98, 0x80000000, v108
	ds_write_b128 v195, v[88:91] offset:40960
	ds_write_b128 v195, v[96:99] offset:32784
	v_pk_mul_f32 v[88:89], v[120:121], v[130:131]
	v_pk_mul_f32 v[90:91], v[122:123], v[108:109]
	ds_write_b128 v195, v[88:91] offset:40976
	v_fma_f32 v88, v92, v116, 0
	v_fmac_f32_e32 v88, v93, v117
	v_fmac_f32_e32 v88, v94, v118
	v_fmac_f32_e32 v88, v95, v119
	v_fmac_f32_e32 v88, v100, v104
	v_fmac_f32_e32 v88, v101, v105
	v_fmac_f32_e32 v88, v102, v106
	v_fmac_f32_e32 v88, v103, v107
	s_nop 1
	v_add_f32_dpp v88, v88, v88 quad_perm:[1,0,3,2] row_mask:0xf bank_mask:0xf bound_ctrl:1
	s_nop 1
	v_add_f32_dpp v88, v88, v88 quad_perm:[2,3,0,1] row_mask:0xf bank_mask:0xf bound_ctrl:1
	s_nop 1
	v_mov_b32_dpp v89, v88 row_half_mirror row_mask:0xf bank_mask:0xf bound_ctrl:1
	s_and_saveexec_b64 s[14:15], s[12:13]
	s_cbranch_execz .LBB0_492
	v_lshlrev_b64 v[90:91], 6, v[128:129]
	v_lshl_add_u64 v[90:91], s[22:23], 0, v[90:91]
	v_add_f32_e32 v88, v88, v89
	global_store_dword v[90:91], v88, off
.LBB0_492:
	s_or_b64 exec, exec, s[14:15]
	s_waitcnt lgkmcnt(0)
	s_barrier
	ds_read_b128 v[104:107], v197 offset:32768
	ds_read_b128 v[112:115], v197 offset:32784
	ds_read_b128 v[88:91], v197 offset:8192
	ds_read_b128 v[96:99], v197 offset:8208
	ds_read_b128 v[92:95], v197 offset:40960
	ds_read_b128 v[100:103], v197 offset:40976
	ds_read_b128 v[108:111], v197 offset:24576
	ds_read_b128 v[116:119], v197 offset:24592
	v_add_u32_e32 v120, 0x4000, v198
	ds_read2_b32 v[130:131], v120 offset1:32
	ds_read_b128 v[120:123], v197
	ds_read_b128 v[124:127], v197 offset:16
	s_mov_b32 s14, 0
	s_waitcnt lgkmcnt(0)
	v_mov_b32_e32 v132, v131
.LBB0_493:
	v_add_u32_e32 v137, s14, v197
	v_add_u32_e32 v136, s14, v148
	v_pk_mul_f32 v[134:135], v[104:105], v[36:37]
	v_pk_mul_f32 v[104:105], v[104:105], v[40:41]
	v_pk_fma_f32 v[134:135], v[38:39], v[106:107], v[134:135]
	v_pk_fma_f32 v[104:105], v[42:43], v[106:107], v[104:105]
	v_pk_fma_f32 v[134:135], v[32:33], v[112:113], v[134:135]
	v_pk_fma_f32 v[104:105], v[44:45], v[112:113], v[104:105]
	v_pk_fma_f32 v[134:135], v[34:35], v[114:115], v[134:135]
	v_pk_fma_f32 v[138:139], v[46:47], v[114:115], v[104:105]
	ds_read_b128 v[104:107], v137 offset:33024
	ds_read_b128 v[112:115], v137 offset:33040
	v_add_f32_e32 v134, v134, v135
	v_add_f32_e32 v135, v138, v139
	v_pk_mul_f32 v[140:141], v[88:89], v[130:131] op_sel_hi:[1,0]
	v_add_f32_dpp v134, v134, v134 quad_perm:[1,0,3,2] row_mask:0xf bank_mask:0xf bound_ctrl:1
	v_add_f32_dpp v135, v135, v135 quad_perm:[1,0,3,2] row_mask:0xf bank_mask:0xf bound_ctrl:1
	v_pk_mul_f32 v[142:143], v[90:91], v[130:131] op_sel_hi:[1,0]
	v_add_f32_dpp v134, v134, v134 quad_perm:[2,3,0,1] row_mask:0xf bank_mask:0xf bound_ctrl:1
	v_add_f32_dpp v135, v135, v135 quad_perm:[2,3,0,1] row_mask:0xf bank_mask:0xf bound_ctrl:1
	v_pk_mul_f32 v[144:145], v[96:97], v[130:131] op_sel_hi:[1,0]
	v_pk_mul_f32 v[146:147], v[98:99], v[130:131] op_sel_hi:[1,0]
	v_pk_mul_f32 v[160:161], v[88:89], v[132:133] op_sel_hi:[1,0]
	v_add_f32_dpp v134, v134, v134 row_half_mirror row_mask:0xf bank_mask:0xf bound_ctrl:1
	v_add_f32_dpp v138, v135, v135 row_half_mirror row_mask:0xf bank_mask:0xf bound_ctrl:1
	v_pk_mul_f32 v[162:163], v[90:91], v[132:133] op_sel_hi:[1,0]
	v_pk_mul_f32 v[164:165], v[96:97], v[132:133] op_sel_hi:[1,0]
	v_pk_mul_f32 v[132:133], v[98:99], v[132:133] op_sel_hi:[1,0]
	ds_read_b128 v[96:99], v137 offset:8448
	ds_read_b128 v[88:91], v137 offset:8464
	ds_read2_b32 v[130:131], v136 offset1:32
	s_waitcnt lgkmcnt(11)
	v_pk_fma_f32 v[140:141], v[134:135], v[92:93], v[140:141] op_sel_hi:[0,1,1]
	v_pk_fma_f32 v[142:143], v[134:135], v[94:95], v[142:143] op_sel_hi:[0,1,1]
	v_pk_fma_f32 v[144:145], v[134:135], v[100:101], v[144:145] op_sel_hi:[0,1,1]
	v_pk_fma_f32 v[134:135], v[134:135], v[102:103], v[146:147] op_sel_hi:[0,1,1]
	v_pk_fma_f32 v[146:147], v[138:139], v[92:93], v[160:161] op_sel_hi:[0,1,1]
	v_pk_fma_f32 v[160:161], v[138:139], v[94:95], v[162:163] op_sel_hi:[0,1,1]
	v_pk_fma_f32 v[132:133], v[138:139], v[102:103], v[132:133] op_sel_hi:[0,1,1]
	s_waitcnt lgkmcnt(10)
	v_pk_fma_f32 v[36:37], v[36:37], v[108:109], v[140:141]
	v_pk_fma_f32 v[108:109], v[40:41], v[108:109], v[146:147]
	v_pk_fma_f32 v[162:163], v[138:139], v[100:101], v[164:165] op_sel_hi:[0,1,1]
	ds_read_b128 v[100:103], v137 offset:41216
	ds_read_b128 v[92:95], v137 offset:41232
	v_pk_fma_f32 v[38:39], v[38:39], v[110:111], v[142:143]
	s_waitcnt lgkmcnt(10)
	v_pk_fma_f32 v[34:35], v[34:35], v[118:119], v[134:135]
	v_pk_fma_f32 v[110:111], v[42:43], v[110:111], v[160:161]
	v_pk_fma_f32 v[118:119], v[46:47], v[118:119], v[132:133]
	v_pk_mul_f32 v[132:133], v[120:121], v[36:37]
	v_pk_mul_f32 v[120:121], v[120:121], v[108:109]
	v_pk_fma_f32 v[32:33], v[32:33], v[116:117], v[144:145]
	v_pk_fma_f32 v[116:117], v[44:45], v[116:117], v[162:163]
	v_pk_fma_f32 v[132:133], v[38:39], v[122:123], v[132:133]
	v_pk_fma_f32 v[120:121], v[110:111], v[122:123], v[120:121]
	s_waitcnt lgkmcnt(9)
	v_pk_fma_f32 v[132:133], v[32:33], v[124:125], v[132:133]
	v_pk_fma_f32 v[120:121], v[116:117], v[124:125], v[120:121]
	v_pk_fma_f32 v[132:133], v[34:35], v[126:127], v[132:133]
	v_pk_fma_f32 v[134:135], v[118:119], v[126:127], v[120:121]
	v_add_f32_e32 v132, v132, v133
	v_add_f32_e32 v133, v134, v135
	ds_read_b128 v[40:43], v137 offset:24832
	v_add_f32_dpp v132, v132, v132 quad_perm:[1,0,3,2] row_mask:0xf bank_mask:0xf bound_ctrl:1
	v_add_f32_dpp v133, v133, v133 quad_perm:[1,0,3,2] row_mask:0xf bank_mask:0xf bound_ctrl:1
	ds_read_b128 v[44:47], v137 offset:24848
	v_add_f32_dpp v132, v132, v132 quad_perm:[2,3,0,1] row_mask:0xf bank_mask:0xf bound_ctrl:1
	v_add_f32_dpp v133, v133, v133 quad_perm:[2,3,0,1] row_mask:0xf bank_mask:0xf bound_ctrl:1
	ds_read_b128 v[124:127], v137 offset:256
	v_add_f32_dpp v132, v132, v132 row_half_mirror row_mask:0xf bank_mask:0xf bound_ctrl:1
	v_add_f32_dpp v133, v133, v133 row_half_mirror row_mask:0xf bank_mask:0xf bound_ctrl:1
	ds_read_b128 v[120:123], v137 offset:272
	ds_write_b32 v136, v132 offset:32512
	ds_write_b32 v136, v133 offset:32640
	s_waitcnt lgkmcnt(12)
	v_pk_mul_f32 v[132:133], v[104:105], v[36:37]
	v_pk_mul_f32 v[104:105], v[104:105], v[108:109]
	v_pk_fma_f32 v[132:133], v[38:39], v[106:107], v[132:133]
	v_pk_fma_f32 v[104:105], v[110:111], v[106:107], v[104:105]
	s_waitcnt lgkmcnt(11)
	v_pk_fma_f32 v[132:133], v[32:33], v[112:113], v[132:133]
	v_pk_fma_f32 v[104:105], v[116:117], v[112:113], v[104:105]
	v_pk_fma_f32 v[132:133], v[34:35], v[114:115], v[132:133]
	v_pk_fma_f32 v[134:135], v[118:119], v[114:115], v[104:105]
	ds_read_b128 v[104:107], v137 offset:33280
	ds_read_b128 v[112:115], v137 offset:33296
	v_add_f32_e32 v132, v132, v133
	v_add_f32_e32 v133, v134, v135
	s_waitcnt lgkmcnt(10)
	v_pk_mul_f32 v[138:139], v[96:97], v[130:131] op_sel_hi:[1,0]
	v_add_f32_dpp v132, v132, v132 quad_perm:[1,0,3,2] row_mask:0xf bank_mask:0xf bound_ctrl:1
	v_add_f32_dpp v133, v133, v133 quad_perm:[1,0,3,2] row_mask:0xf bank_mask:0xf bound_ctrl:1
	v_pk_mul_f32 v[140:141], v[98:99], v[130:131] op_sel_hi:[1,0]
	v_pk_mul_f32 v[142:143], v[88:89], v[130:131] op_sel_hi:[1,0]
	v_pk_mul_f32 v[144:145], v[90:91], v[130:131] op_sel_hi:[1,0]
	v_mov_b32_e32 v130, v131
	v_add_f32_dpp v132, v132, v132 quad_perm:[2,3,0,1] row_mask:0xf bank_mask:0xf bound_ctrl:1
	v_add_f32_dpp v133, v133, v133 quad_perm:[2,3,0,1] row_mask:0xf bank_mask:0xf bound_ctrl:1
	v_pk_mul_f32 v[146:147], v[96:97], v[130:131] op_sel_hi:[1,0]
	v_add_f32_dpp v132, v132, v132 row_half_mirror row_mask:0xf bank_mask:0xf bound_ctrl:1
	v_add_f32_dpp v134, v133, v133 row_half_mirror row_mask:0xf bank_mask:0xf bound_ctrl:1
	v_pk_mul_f32 v[160:161], v[98:99], v[130:131] op_sel_hi:[1,0]
	s_waitcnt lgkmcnt(8)
	v_pk_fma_f32 v[138:139], v[132:133], v[100:101], v[138:139] op_sel_hi:[0,1,1]
	v_pk_fma_f32 v[140:141], v[132:133], v[102:103], v[140:141] op_sel_hi:[0,1,1]
	v_pk_fma_f32 v[142:143], v[132:133], v[92:93], v[142:143] op_sel_hi:[0,1,1]
	v_pk_fma_f32 v[132:133], v[132:133], v[94:95], v[144:145] op_sel_hi:[0,1,1]
	v_pk_fma_f32 v[144:145], v[134:135], v[100:101], v[146:147] op_sel_hi:[0,1,1]
	v_pk_mul_f32 v[162:163], v[88:89], v[130:131] op_sel_hi:[1,0]
	v_pk_fma_f32 v[146:147], v[134:135], v[102:103], v[160:161] op_sel_hi:[0,1,1]
	s_waitcnt lgkmcnt(7)
	v_pk_fma_f32 v[36:37], v[36:37], v[40:41], v[138:139]
	v_pk_fma_f32 v[40:41], v[108:109], v[40:41], v[144:145]
	v_pk_mul_f32 v[164:165], v[90:91], v[130:131] op_sel_hi:[1,0]
	ds_read_b128 v[88:91], v137 offset:8704
	ds_read_b128 v[96:99], v137 offset:8720
	ds_read2_b32 v[130:131], v136 offset0:64 offset1:96
	v_pk_fma_f32 v[160:161], v[134:135], v[92:93], v[162:163] op_sel_hi:[0,1,1]
	v_pk_fma_f32 v[38:39], v[38:39], v[42:43], v[140:141]
	s_waitcnt lgkmcnt(8)
	v_pk_fma_f32 v[34:35], v[34:35], v[46:47], v[132:133]
	v_pk_fma_f32 v[42:43], v[110:111], v[42:43], v[146:147]
	v_pk_mul_f32 v[132:133], v[124:125], v[36:37]
	v_pk_mul_f32 v[124:125], v[124:125], v[40:41]
	v_pk_fma_f32 v[134:135], v[134:135], v[94:95], v[164:165] op_sel_hi:[0,1,1]
	ds_read_b128 v[92:95], v137 offset:41472
	ds_read_b128 v[100:103], v137 offset:41488
	v_pk_fma_f32 v[32:33], v[32:33], v[44:45], v[142:143]
	v_pk_fma_f32 v[44:45], v[116:117], v[44:45], v[160:161]
	v_pk_fma_f32 v[132:133], v[38:39], v[126:127], v[132:133]
	v_pk_fma_f32 v[124:125], v[42:43], v[126:127], v[124:125]
	v_pk_fma_f32 v[46:47], v[118:119], v[46:47], v[134:135]
	s_waitcnt lgkmcnt(9)
	v_pk_fma_f32 v[132:133], v[32:33], v[120:121], v[132:133]
	v_pk_fma_f32 v[120:121], v[44:45], v[120:121], v[124:125]
	v_pk_fma_f32 v[132:133], v[34:35], v[122:123], v[132:133]
	v_pk_fma_f32 v[134:135], v[46:47], v[122:123], v[120:121]
	v_add_f32_e32 v132, v132, v133
	v_add_f32_e32 v133, v134, v135
	ds_read_b128 v[108:111], v137 offset:25088
	v_add_f32_dpp v132, v132, v132 quad_perm:[1,0,3,2] row_mask:0xf bank_mask:0xf bound_ctrl:1
	v_add_f32_dpp v133, v133, v133 quad_perm:[1,0,3,2] row_mask:0xf bank_mask:0xf bound_ctrl:1
	ds_read_b128 v[116:119], v137 offset:25104
	v_add_f32_dpp v132, v132, v132 quad_perm:[2,3,0,1] row_mask:0xf bank_mask:0xf bound_ctrl:1
	v_add_f32_dpp v133, v133, v133 quad_perm:[2,3,0,1] row_mask:0xf bank_mask:0xf bound_ctrl:1
	ds_read_b128 v[120:123], v137 offset:512
	v_add_f32_dpp v132, v132, v132 row_half_mirror row_mask:0xf bank_mask:0xf bound_ctrl:1
	v_add_f32_dpp v133, v133, v133 row_half_mirror row_mask:0xf bank_mask:0xf bound_ctrl:1
	ds_read_b128 v[124:127], v137 offset:528
	ds_write_b32 v136, v132 offset:32768
	ds_write_b32 v136, v133 offset:32896
	s_waitcnt lgkmcnt(8)
	v_mov_b32_e32 v132, v131
	s_addk_i32 s14, 0x200
	s_cmpk_eq_i32 s14, 0x2000
	s_cbranch_scc0 .LBB0_493
	s_waitcnt lgkmcnt(0)
	s_barrier
	ds_read_b128 v[88:91], v195 offset:49152
	ds_read_b128 v[92:95], v195 offset:49168
	v_mov_b64_e32 v[106:107], v[86:87]
	v_mov_b64_e32 v[98:99], v[74:75]
	v_mov_b64_e32 v[110:111], v[78:79]
	s_waitcnt lgkmcnt(1)
	v_cvt_pk_bf16_f32 v88, v88, v89
	v_cvt_pk_bf16_f32 v89, v90, v91
	s_waitcnt lgkmcnt(0)
	v_cvt_pk_bf16_f32 v90, v92, v93
	v_lshlrev_b64 v[92:93], 10, v[128:129]
	v_cvt_pk_bf16_f32 v91, v94, v95
	v_lshl_add_u64 v[92:93], v[150:151], 0, v[92:93]
	global_store_dwordx4 v[92:93], v[88:91], off
	v_mov_b64_e32 v[114:115], v[82:83]
	s_cmp_eq_u32 s2, 64
	v_mov_b64_e32 v[90:91], v[70:71]
	v_mov_b64_e32 v[104:105], v[84:85]
	v_mov_b64_e32 v[88:89], v[68:69]
	v_mov_b64_e32 v[96:97], v[72:73]
	v_mov_b64_e32 v[108:109], v[76:77]
	v_mov_b64_e32 v[112:113], v[80:81]
	s_mov_b32 s15, s2
	s_cbranch_scc0 .LBB0_481
	s_setprio 0
	v_mov_b32_e32 v158, v222
	v_mov_b32_e32 v159, v223
	s_barrier
	s_branch .LBB0_395
